# v88 + int8 MFMA blocks: each accumulator pair emitted in the k-order whose first MFMA shares an operand with the previous MFMA (i32 accumulate is order-independent)
# speedup vs baseline: 1.0189x; 1.0018x over previous
; #define PG8_STAGE(bufoff, gbase, voff) do { _Pragma("unroll") for (int _i = 0; _i < 2; ++_i) \
;         __builtin_amdgcn_global_load_lds((const unsigned*)((const char*)(gbase) + (voff)[_i]), (PG8_LAS unsigned*)(lds + (bufoff) + ldsw + _i * 8192), 16, 0, 0); } while (0)
; #define PG8_LDA(dst, b, h) do { _Pragma("unroll") for (int m = 0; m < 4; ++m) _Pragma("unroll") for (int k = 0; k < 2; ++k) dst[m][k] = *(const PG8_LAS bf16x8*)(lds + PG8_SA(b, h) + aoff + m * 2048 + k * 1024); } while (0)
; #define PG8_LDB(dst, b, h) do { _Pragma("unroll") for (int n = 0; n < 2; ++n) _Pragma("unroll") for (int k = 0; k < 2; ++k) dst[n][k] = *(const PG8_LAS bf16x8*)(lds + PG8_SB(b, h) + boff + n * 2048 + k * 1024); } while (0)
; #define PG8_MMA(ai, bj, At, Bt) do { __builtin_amdgcn_s_setprio(1); _Pragma("unroll") for (int m = 0; m < 4; ++m) _Pragma("unroll") for (int n = 0; n < 2; ++n) _Pragma("unroll") for (int k = 0; k < 2; ++k) \
;         acc[ai][bj][m][n] = mma16<Epi::I8>(Bt[n][k], At[m][k], acc[ai][bj][m][n]); __builtin_amdgcn_s_setprio(0); } while (0)
; #define PG8_WAIT_V(n) asm volatile("s_waitcnt vmcnt(" #n ")" ::: "memory")
; #define PG8_WAIT_L(n) asm volatile("s_waitcnt lgkmcnt(" #n ")" ::: "memory")
; template <class Epi, class Sched, bool ALIGN_EPI = false, bool SP2 = false>
; __device__ __forceinline__ void gemm_phase(PG8_LAS unsigned char* lds, const Gemm g, const Sched& S, const Epi& E) {
;     ...
;         for (int t = 0; t < nt; t += 2) {
;             const bool last = (t == nt - 2);
;             const char* a1 = cA + (size_t)(t + 1) * kstep;
;             const char* a2 = last ? nA : cA + (size_t)(t + 2) * kstep; const char* b2 = last ? nB : cB + (size_t)(t + 2) * kstep;
;             const char* a3 = a2 + kstep; const char* b3 = b2 + kstep;
;             if (last && has_next) S.a_ready(nxt);
;             if constexpr (SP2) {
;             PG8_LDB(B0, 0, 0); PG8_LDB(B1, 0, 1); PG8_SCHED; PG8_LDA(At, 0, 0); PG8_STAGE(PG8_SA(1, 1), a1 + hstep, voffA);
;             PG8_WAIT_V(8); PG8_WAIT_L(0); PG8_BAR; PG8_MMA(0, 0, At, B0); PG8_MMA(0, 1, At, B1); PG8_BAR; PG8_SCHED;
;             PG8_LDA(At, 0, 1); PG8_STAGE(PG8_SB(0, 0), b2, voffB); PG8_STAGE(PG8_SB(0, 1), b2 + hstep, voffB); PG8_STAGE(PG8_SA(0, 0), a2, voffA);
;             PG8_WAIT_V(8); PG8_WAIT_L(0); PG8_BAR; PG8_MMA(1, 0, At, B0); PG8_MMA(1, 1, At, B1); PG8_BAR; PG8_SCHED;
.Lpeel80:
	s_add_u32 s8, s0, 0x100
	s_addc_u32 s9, s1, 0
	s_add_i32 vcc_hi, 0, 0x10000
	s_cmp_eq_u32 vcc_lo, 12
	s_cselect_b32 s13, s66, s9
	s_cselect_b32 s12, s67, s8
	s_cselect_b32 s7, s82, s97
	s_cselect_b32 s6, s83, s96
	s_add_i32 s4, 0, 0x14000
	v_add_u32_e32 v38, vcc_hi, v242
	v_add_u32_e32 v158, s4, v242
	ds_read_b128 v[18:21], v38
	ds_read_b128 v[22:25], v38 offset:1024
	ds_read_b128 v[34:37], v38 offset:2048
	ds_read_b128 v[38:41], v38 offset:3072
	ds_read_b128 v[130:133], v158
	ds_read_b128 v[134:137], v158 offset:1024
	ds_read_b128 v[154:157], v158 offset:2048
	ds_read_b128 v[158:161], v158 offset:3072
	s_add_i32 m0, s11, 0xc000
	ds_read_b128 v[162:165], v243
	ds_read_b128 v[166:169], v243 offset:1024
	ds_read_b128 v[170:173], v243 offset:2048
	ds_read_b128 v[174:177], v243 offset:3072
	ds_read_b128 v[178:181], v243 offset:4096
	ds_read_b128 v[182:185], v243 offset:5120
	ds_read_b128 v[186:189], v243 offset:6144
	ds_read_b128 v[190:193], v243 offset:7168
	global_load_lds_dwordx4 v216, s[0:1]
	s_add_i32 m0, s11, 0xe000
	s_nop 0
	global_load_lds_dwordx4 v218, s[0:1]
	s_waitcnt vmcnt(8)
	s_waitcnt lgkmcnt(0)
	s_barrier
	s_waitcnt lgkmcnt(0)
	v_mfma_i32_16x16x64_i8 v[150:153], v[18:21], v[162:165], 0
	v_mfma_i32_16x16x64_i8 v[150:153], v[22:25], v[166:169], v[150:153]
	v_mfma_i32_16x16x64_i8 v[146:149], v[38:41], v[166:169], 0
	v_mfma_i32_16x16x64_i8 v[146:149], v[34:37], v[162:165], v[146:149]
	v_mfma_i32_16x16x64_i8 v[110:113], v[34:37], v[170:173], 0
	v_mfma_i32_16x16x64_i8 v[110:113], v[38:41], v[174:177], v[110:113]
	v_mfma_i32_16x16x64_i8 v[118:121], v[22:25], v[174:177], 0
	v_mfma_i32_16x16x64_i8 v[118:121], v[18:21], v[170:173], v[118:121]
	v_mfma_i32_16x16x64_i8 v[54:57], v[18:21], v[178:181], 0
	v_mfma_i32_16x16x64_i8 v[54:57], v[22:25], v[182:185], v[54:57]
	v_mfma_i32_16x16x64_i8 v[30:33], v[38:41], v[182:185], 0
	v_mfma_i32_16x16x64_i8 v[30:33], v[34:37], v[178:181], v[30:33]
	v_mfma_i32_16x16x64_i8 v[58:61], v[34:37], v[186:189], 0
	v_mfma_i32_16x16x64_i8 v[58:61], v[38:41], v[190:193], v[58:61]
	v_mfma_i32_16x16x64_i8 v[94:97], v[22:25], v[190:193], 0
	v_mfma_i32_16x16x64_i8 v[94:97], v[18:21], v[186:189], v[94:97]
	v_mfma_i32_16x16x64_i8 v[62:65], v[154:157], v[186:189], 0
	v_mfma_i32_16x16x64_i8 v[62:65], v[158:161], v[190:193], v[62:65]
	v_mfma_i32_16x16x64_i8 v[138:141], v[158:161], v[166:169], 0
	v_mfma_i32_16x16x64_i8 v[138:141], v[154:157], v[162:165], v[138:141]
	v_mfma_i32_16x16x64_i8 v[142:145], v[130:133], v[162:165], 0
	v_mfma_i32_16x16x64_i8 v[142:145], v[134:137], v[166:169], v[142:145]
	v_mfma_i32_16x16x64_i8 v[102:105], v[134:137], v[174:177], 0
	v_mfma_i32_16x16x64_i8 v[102:105], v[130:133], v[170:173], v[102:105]
	v_mfma_i32_16x16x64_i8 v[98:101], v[154:157], v[170:173], 0
	v_mfma_i32_16x16x64_i8 v[98:101], v[158:161], v[174:177], v[98:101]
	v_mfma_i32_16x16x64_i8 v[26:29], v[158:161], v[182:185], 0
	v_mfma_i32_16x16x64_i8 v[26:29], v[154:157], v[178:181], v[26:29]
	v_mfma_i32_16x16x64_i8 v[42:45], v[130:133], v[178:181], 0
	v_mfma_i32_16x16x64_i8 v[42:45], v[134:137], v[182:185], v[42:45]
	v_mfma_i32_16x16x64_i8 v[78:81], v[134:137], v[190:193], 0
	v_mfma_i32_16x16x64_i8 v[78:81], v[130:133], v[186:189], v[78:81]
	s_barrier
	s_add_i32 s0, vcc_hi, s69
	v_lshl_add_u64 v[198:199], s[6:7], 0, v[0:1]
	s_mov_b32 m0, s0
	ds_read_b128 v[162:165], v243 offset:16384
	ds_read_b128 v[166:169], v243 offset:17408
	ds_read_b128 v[170:173], v243 offset:18432
	ds_read_b128 v[174:177], v243 offset:19456
	ds_read_b128 v[178:181], v243 offset:20480
	ds_read_b128 v[182:185], v243 offset:21504
	ds_read_b128 v[186:189], v243 offset:22528
	ds_read_b128 v[190:193], v243 offset:23552
	global_load_lds_dwordx4 v[198:199], off
	s_add_i32 m0, s0, 0x2000
	s_add_u32 s0, s6, 0x40000
	v_lshl_add_u64 v[200:201], s[6:7], 0, v[214:215]
	s_addc_u32 s1, s7, 0
	s_add_i32 s4, s4, s69
	global_load_lds_dwordx4 v[200:201], off
	s_mov_b32 m0, s4
	v_lshl_add_u64 v[206:207], s[12:13], 0, v[210:211]
	global_load_lds_dwordx4 v0, s[0:1]
	s_add_i32 m0, s4, 0x2000
	v_lshl_add_u64 v[220:221], s[12:13], 0, v[212:213]
	global_load_lds_dwordx4 v214, s[0:1]
	s_mov_b32 m0, s11
	s_nop 0
	global_load_lds_dwordx4 v[206:207], off
	s_mov_b32 m0, s71
	s_nop 0
	global_load_lds_dwordx4 v[220:221], off
	s_waitcnt vmcnt(8)
	s_waitcnt lgkmcnt(0)
	s_barrier
	s_waitcnt lgkmcnt(0)
	v_mfma_i32_16x16x64_i8 v[106:109], v[18:21], v[162:165], 0
	v_mfma_i32_16x16x64_i8 v[106:109], v[22:25], v[166:169], v[106:109]
	v_mfma_i32_16x16x64_i8 v[46:49], v[34:37], v[162:165], 0
	v_mfma_i32_16x16x64_i8 v[46:49], v[38:41], v[166:169], v[46:49]
	v_mfma_i32_16x16x64_i8 v[6:9], v[34:37], v[170:173], 0
	v_mfma_i32_16x16x64_i8 v[6:9], v[38:41], v[174:177], v[6:9]
	v_mfma_i32_16x16x64_i8 v[14:17], v[18:21], v[170:173], 0
	v_mfma_i32_16x16x64_i8 v[14:17], v[22:25], v[174:177], v[14:17]
	v_mfma_i32_16x16x64_i8 v[90:93], v[18:21], v[178:181], 0
	v_mfma_i32_16x16x64_i8 v[90:93], v[22:25], v[182:185], v[90:93]
	v_mfma_i32_16x16x64_i8 v[86:89], v[34:37], v[178:181], 0
	v_mfma_i32_16x16x64_i8 v[86:89], v[38:41], v[182:185], v[86:89]
	v_mfma_i32_16x16x64_i8 v[18:21], v[18:21], v[186:189], 0
	v_mfma_i32_16x16x64_i8 v[18:21], v[22:25], v[190:193], v[18:21]
	v_mfma_i32_16x16x64_i8 v[22:25], v[34:37], v[186:189], 0
	v_mfma_i32_16x16x64_i8 v[22:25], v[38:41], v[190:193], v[22:25]
	v_mfma_i32_16x16x64_i8 v[38:41], v[154:157], v[162:165], 0
	v_mfma_i32_16x16x64_i8 v[38:41], v[158:161], v[166:169], v[38:41]
	v_mfma_i32_16x16x64_i8 v[2:5], v[154:157], v[170:173], 0
	v_mfma_i32_16x16x64_i8 v[2:5], v[158:161], v[174:177], v[2:5]
	v_mfma_i32_16x16x64_i8 v[10:13], v[130:133], v[170:173], 0
	v_mfma_i32_16x16x64_i8 v[10:13], v[134:137], v[174:177], v[10:13]
	v_mfma_i32_16x16x64_i8 v[50:53], v[130:133], v[178:181], 0
	v_mfma_i32_16x16x64_i8 v[82:85], v[134:137], v[182:185], v[50:53]
	v_mfma_i32_16x16x64_i8 v[34:37], v[130:133], v[162:165], 0
	v_mfma_i32_16x16x64_i8 v[34:37], v[134:137], v[166:169], v[34:37]
	v_mfma_i32_16x16x64_i8 v[50:53], v[154:157], v[178:181], 0
	v_mfma_i32_16x16x64_i8 v[74:77], v[158:161], v[182:185], v[50:53]
	v_mfma_i32_16x16x64_i8 v[50:53], v[130:133], v[186:189], 0
	v_mfma_i32_16x16x64_i8 v[122:125], v[134:137], v[190:193], v[50:53]
	v_mfma_i32_16x16x64_i8 v[50:53], v[154:157], v[186:189], 0
	v_mfma_i32_16x16x64_i8 v[70:73], v[158:161], v[190:193], v[50:53]
	s_barrier
; #define PG8_STAGE(bufoff, gbase, voff) do { _Pragma("unroll") for (int _i = 0; _i < 2; ++_i) \
;         __builtin_amdgcn_global_load_lds((const unsigned*)((const char*)(gbase) + (voff)[_i]), (PG8_LAS unsigned*)(lds + (bufoff) + ldsw + _i * 8192), 16, 0, 0); } while (0)
; #define PG8_LDA(dst, b, h) do { _Pragma("unroll") for (int m = 0; m < 4; ++m) _Pragma("unroll") for (int k = 0; k < 2; ++k) dst[m][k] = *(const PG8_LAS bf16x8*)(lds + PG8_SA(b, h) + aoff + m * 2048 + k * 1024); } while (0)
; #define PG8_LDB(dst, b, h) do { _Pragma("unroll") for (int n = 0; n < 2; ++n) _Pragma("unroll") for (int k = 0; k < 2; ++k) dst[n][k] = *(const PG8_LAS bf16x8*)(lds + PG8_SB(b, h) + boff + n * 2048 + k * 1024); } while (0)
; #define PG8_MMA(ai, bj, At, Bt) do { __builtin_amdgcn_s_setprio(1); _Pragma("unroll") for (int m = 0; m < 4; ++m) _Pragma("unroll") for (int n = 0; n < 2; ++n) _Pragma("unroll") for (int k = 0; k < 2; ++k) \
;         acc[ai][bj][m][n] = mma16<Epi::I8>(Bt[n][k], At[m][k], acc[ai][bj][m][n]); __builtin_amdgcn_s_setprio(0); } while (0)
; #define PG8_WAIT_V(n) asm volatile("s_waitcnt vmcnt(" #n ")" ::: "memory")
; #define PG8_WAIT_L(n) asm volatile("s_waitcnt lgkmcnt(" #n ")" ::: "memory")
; #define PG8_BAR __builtin_amdgcn_s_barrier()
; #define PG8_SCHED __builtin_amdgcn_sched_barrier(0)
; template <class Epi, class Sched, bool ALIGN_EPI = false, bool SP2 = false>
; __device__ __forceinline__ void gemm_phase(PG8_LAS unsigned char* lds, const Gemm g, const Sched& S, const Epi& E) {
;     ...
;             PG8_LDB(B0, 1, 0); PG8_LDB(B1, 1, 1); PG8_SCHED; PG8_LDA(At, 1, 0); PG8_STAGE(PG8_SA(0, 1), a2 + hstep, voffA);
;             PG8_WAIT_V(8); PG8_WAIT_L(0); PG8_BAR; PG8_MMA(0, 0, At, B0); PG8_MMA(0, 1, At, B1); PG8_BAR; PG8_SCHED;
;             PG8_LDA(At, 1, 1); PG8_STAGE(PG8_SB(1, 0), b3, voffB); PG8_STAGE(PG8_SB(1, 1), b3 + hstep, voffB); PG8_STAGE(PG8_SA(1, 0), a3, voffA);
;             PG8_WAIT_V(8); PG8_WAIT_L(0); PG8_BAR; PG8_MMA(1, 0, At, B0); PG8_MMA(1, 1, At, B1); PG8_BAR; PG8_SCHED;
	s_add_i32 s4, 0, 0x18000
	v_add_u32_e32 v126, s4, v242
	s_add_i32 s5, 0, 0x1c000
	ds_read_b128 v[50:53], v126
	ds_read_b128 v[66:69], v126 offset:1024
	ds_read_b128 v[114:117], v126 offset:2048
	ds_read_b128 v[130:133], v126 offset:3072
	v_add_u32_e32 v126, s5, v242
	ds_read_b128 v[134:137], v126
	ds_read_b128 v[154:157], v126 offset:1024
	ds_read_b128 v[158:161], v126 offset:2048
	ds_read_b128 v[162:165], v126 offset:3072
	s_add_u32 s0, s12, 0x40000
	s_addc_u32 s1, s13, 0
	s_mov_b32 m0, s80
	ds_read_b128 v[126:129], v243 offset:32768
	ds_read_b128 v[166:169], v243 offset:33792
	ds_read_b128 v[170:173], v243 offset:34816
	ds_read_b128 v[174:177], v243 offset:35840
	ds_read_b128 v[178:181], v243 offset:36864
	ds_read_b128 v[182:185], v243 offset:37888
	ds_read_b128 v[186:189], v243 offset:38912
	ds_read_b128 v[190:193], v243 offset:39936
	global_load_lds_dwordx4 v210, s[0:1]
	s_mov_b32 m0, s81
	s_nop 0
	global_load_lds_dwordx4 v212, s[0:1]
	s_waitcnt vmcnt(8)
	s_waitcnt lgkmcnt(0)
	s_barrier
	s_waitcnt lgkmcnt(0)
	v_mfma_i32_16x16x64_i8 v[150:153], v[50:53], v[126:129], v[150:153]
	v_mfma_i32_16x16x64_i8 v[150:153], v[66:69], v[166:169], v[150:153]
	v_mfma_i32_16x16x64_i8 v[146:149], v[114:117], v[126:129], v[146:149]
	v_mfma_i32_16x16x64_i8 v[146:149], v[130:133], v[166:169], v[146:149]
	v_mfma_i32_16x16x64_i8 v[110:113], v[114:117], v[170:173], v[110:113]
	v_mfma_i32_16x16x64_i8 v[110:113], v[130:133], v[174:177], v[110:113]
	v_mfma_i32_16x16x64_i8 v[118:121], v[50:53], v[170:173], v[118:121]
	v_mfma_i32_16x16x64_i8 v[118:121], v[66:69], v[174:177], v[118:121]
	v_mfma_i32_16x16x64_i8 v[54:57], v[50:53], v[178:181], v[54:57]
	v_mfma_i32_16x16x64_i8 v[54:57], v[66:69], v[182:185], v[54:57]
	v_mfma_i32_16x16x64_i8 v[30:33], v[114:117], v[178:181], v[30:33]
	v_mfma_i32_16x16x64_i8 v[30:33], v[130:133], v[182:185], v[30:33]
	v_mfma_i32_16x16x64_i8 v[58:61], v[114:117], v[186:189], v[58:61]
	v_mfma_i32_16x16x64_i8 v[58:61], v[130:133], v[190:193], v[58:61]
	v_mfma_i32_16x16x64_i8 v[94:97], v[50:53], v[186:189], v[94:97]
	v_mfma_i32_16x16x64_i8 v[94:97], v[66:69], v[190:193], v[94:97]
	v_mfma_i32_16x16x64_i8 v[142:145], v[134:137], v[126:129], v[142:145]
	v_mfma_i32_16x16x64_i8 v[142:145], v[154:157], v[166:169], v[142:145]
	v_mfma_i32_16x16x64_i8 v[126:129], v[158:161], v[126:129], v[138:141]
	v_mfma_i32_16x16x64_i8 v[138:141], v[162:165], v[166:169], v[126:129]
	v_mfma_i32_16x16x64_i8 v[98:101], v[158:161], v[170:173], v[98:101]
	v_mfma_i32_16x16x64_i8 v[98:101], v[162:165], v[174:177], v[98:101]
	v_mfma_i32_16x16x64_i8 v[102:105], v[134:137], v[170:173], v[102:105]
	v_mfma_i32_16x16x64_i8 v[102:105], v[154:157], v[174:177], v[102:105]
	v_mfma_i32_16x16x64_i8 v[42:45], v[134:137], v[178:181], v[42:45]
	v_mfma_i32_16x16x64_i8 v[42:45], v[154:157], v[182:185], v[42:45]
	v_mfma_i32_16x16x64_i8 v[26:29], v[158:161], v[178:181], v[26:29]
	v_mfma_i32_16x16x64_i8 v[26:29], v[162:165], v[182:185], v[26:29]
	v_mfma_i32_16x16x64_i8 v[62:65], v[158:161], v[186:189], v[62:65]
	v_mfma_i32_16x16x64_i8 v[62:65], v[162:165], v[190:193], v[62:65]
	v_mfma_i32_16x16x64_i8 v[78:81], v[134:137], v[186:189], v[78:81]
	v_mfma_i32_16x16x64_i8 v[78:81], v[154:157], v[190:193], v[78:81]
	s_barrier
	s_add_i32 s0, s4, s69
	v_lshl_add_u64 v[126:127], v[198:199], 0, s[92:93]
	s_mov_b32 m0, s0
	ds_read_b128 v[166:169], v243 offset:49152
	ds_read_b128 v[170:173], v243 offset:50176
	ds_read_b128 v[174:177], v243 offset:51200
	ds_read_b128 v[178:181], v243 offset:52224
	ds_read_b128 v[182:185], v243 offset:53248
	ds_read_b128 v[186:189], v243 offset:54272
	ds_read_b128 v[190:193], v243 offset:55296
	ds_read_b128 v[194:197], v243 offset:56320
	global_load_lds_dwordx4 v[126:127], off
	s_add_i32 m0, s0, 0x2000
	s_add_u32 s0, s6, 0x40080
	v_lshl_add_u64 v[126:127], v[200:201], 0, s[92:93]
	s_addc_u32 s1, s7, 0
	s_add_i32 s4, s5, s69
	global_load_lds_dwordx4 v[126:127], off
	s_mov_b32 m0, s4
	s_nop 0
	global_load_lds_dwordx4 v0, s[0:1]
	s_add_i32 m0, s4, 0x2000
	s_nop 0
	global_load_lds_dwordx4 v214, s[0:1]
	v_lshl_add_u64 v[126:127], v[206:207], 0, s[92:93]
	s_mov_b32 m0, s84
	s_nop 0
	global_load_lds_dwordx4 v[126:127], off
	v_lshl_add_u64 v[126:127], v[220:221], 0, s[92:93]
	s_mov_b32 m0, s85
	s_nop 0
	global_load_lds_dwordx4 v[126:127], off
	s_waitcnt vmcnt(8)
	s_waitcnt lgkmcnt(0)
	s_barrier
	s_waitcnt lgkmcnt(0)
	v_mfma_i32_16x16x64_i8 v[18:21], v[50:53], v[190:193], v[18:21]
	v_mfma_i32_16x16x64_i8 v[126:129], v[66:69], v[194:197], v[18:21]
	v_mfma_i32_16x16x64_i8 v[106:109], v[50:53], v[166:169], v[106:109]
	v_mfma_i32_16x16x64_i8 v[106:109], v[66:69], v[170:173], v[106:109]
	v_mfma_i32_16x16x64_i8 v[46:49], v[114:117], v[166:169], v[46:49]
	v_mfma_i32_16x16x64_i8 v[46:49], v[130:133], v[170:173], v[46:49]
	v_mfma_i32_16x16x64_i8 v[6:9], v[114:117], v[174:177], v[6:9]
	v_mfma_i32_16x16x64_i8 v[6:9], v[130:133], v[178:181], v[6:9]
	v_mfma_i32_16x16x64_i8 v[14:17], v[50:53], v[174:177], v[14:17]
	v_mfma_i32_16x16x64_i8 v[14:17], v[66:69], v[178:181], v[14:17]
	v_mfma_i32_16x16x64_i8 v[90:93], v[50:53], v[182:185], v[90:93]
	v_mfma_i32_16x16x64_i8 v[90:93], v[66:69], v[186:189], v[90:93]
	v_mfma_i32_16x16x64_i8 v[86:89], v[114:117], v[182:185], v[86:89]
	v_mfma_i32_16x16x64_i8 v[86:89], v[130:133], v[186:189], v[86:89]
	v_mfma_i32_16x16x64_i8 v[18:21], v[114:117], v[190:193], v[22:25]
	v_mfma_i32_16x16x64_i8 v[66:69], v[130:133], v[194:197], v[18:21]
	v_mfma_i32_16x16x64_i8 v[18:21], v[134:137], v[166:169], v[34:37]
	v_mfma_i32_16x16x64_i8 v[114:117], v[154:157], v[170:173], v[18:21]
	v_mfma_i32_16x16x64_i8 v[10:13], v[134:137], v[174:177], v[10:13]
	v_mfma_i32_16x16x64_i8 v[10:13], v[154:157], v[178:181], v[10:13]
	v_mfma_i32_16x16x64_i8 v[2:5], v[158:161], v[174:177], v[2:5]
	v_mfma_i32_16x16x64_i8 v[2:5], v[162:165], v[178:181], v[2:5]
	v_mfma_i32_16x16x64_i8 v[18:21], v[158:161], v[166:169], v[38:41]
	v_mfma_i32_16x16x64_i8 v[50:53], v[162:165], v[170:173], v[18:21]
	v_mfma_i32_16x16x64_i8 v[18:21], v[134:137], v[182:185], v[82:85]
	v_mfma_i32_16x16x64_i8 v[82:85], v[154:157], v[186:189], v[18:21]
	v_mfma_i32_16x16x64_i8 v[18:21], v[158:161], v[182:185], v[74:77]
	v_mfma_i32_16x16x64_i8 v[74:77], v[162:165], v[186:189], v[18:21]
	v_mfma_i32_16x16x64_i8 v[18:21], v[134:137], v[190:193], v[122:125]
	v_mfma_i32_16x16x64_i8 v[122:125], v[154:157], v[194:197], v[18:21]
	v_mfma_i32_16x16x64_i8 v[18:21], v[158:161], v[190:193], v[70:73]
	v_mfma_i32_16x16x64_i8 v[70:73], v[162:165], v[194:197], v[18:21]
	s_barrier
	s_add_i32 vcc_lo, vcc_lo, 2
	s_add_u32 s96, s96, 0x100
	s_addc_u32 s97, s97, 0
	s_cmp_gt_u32 vcc_lo, 13
	s_mov_b64 s[0:1], s[8:9]
	s_cbranch_scc0 .LBB0_80
	s_branch .Lpeelx80
; #define PG8_STAGE(bufoff, gbase, voff) do { _Pragma("unroll") for (int _i = 0; _i < 2; ++_i) \
;         __builtin_amdgcn_global_load_lds((const unsigned*)((const char*)(gbase) + (voff)[_i]), (PG8_LAS unsigned*)(lds + (bufoff) + ldsw + _i * 8192), 16, 0, 0); } while (0)
; #define PG8_LDA(dst, b, h) do { _Pragma("unroll") for (int m = 0; m < 4; ++m) _Pragma("unroll") for (int k = 0; k < 2; ++k) dst[m][k] = *(const PG8_LAS bf16x8*)(lds + PG8_SA(b, h) + aoff + m * 2048 + k * 1024); } while (0)
; #define PG8_LDB(dst, b, h) do { _Pragma("unroll") for (int n = 0; n < 2; ++n) _Pragma("unroll") for (int k = 0; k < 2; ++k) dst[n][k] = *(const PG8_LAS bf16x8*)(lds + PG8_SB(b, h) + boff + n * 2048 + k * 1024); } while (0)
; #define PG8_MMA(ai, bj, At, Bt) do { __builtin_amdgcn_s_setprio(1); _Pragma("unroll") for (int m = 0; m < 4; ++m) _Pragma("unroll") for (int n = 0; n < 2; ++n) _Pragma("unroll") for (int k = 0; k < 2; ++k) \
;         acc[ai][bj][m][n] = mma16<Epi::I8>(Bt[n][k], At[m][k], acc[ai][bj][m][n]); __builtin_amdgcn_s_setprio(0); } while (0)
; #define PG8_WAIT_V(n) asm volatile("s_waitcnt vmcnt(" #n ")" ::: "memory")
; #define PG8_WAIT_L(n) asm volatile("s_waitcnt lgkmcnt(" #n ")" ::: "memory")
; template <class Epi, class Sched, bool ALIGN_EPI = false, bool SP2 = false>
; __device__ __forceinline__ void gemm_phase(PG8_LAS unsigned char* lds, const Gemm g, const Sched& S, const Epi& E) {
;     ...
;         for (int t = 0; t < nt; t += 2) {
;             const bool last = (t == nt - 2);
;             const char* a1 = cA + (size_t)(t + 1) * kstep;
;             const char* a2 = last ? nA : cA + (size_t)(t + 2) * kstep; const char* b2 = last ? nB : cB + (size_t)(t + 2) * kstep;
;             const char* a3 = a2 + kstep; const char* b3 = b2 + kstep;
;             if (last && has_next) S.a_ready(nxt);
;             if constexpr (SP2) {
;             PG8_LDB(B0, 0, 0); PG8_LDB(B1, 0, 1); PG8_SCHED; PG8_LDA(At, 0, 0); PG8_STAGE(PG8_SA(1, 1), a1 + hstep, voffA);
;             PG8_WAIT_V(8); PG8_WAIT_L(0); PG8_BAR; PG8_MMA(0, 0, At, B0); PG8_MMA(0, 1, At, B1); PG8_BAR; PG8_SCHED;
;             PG8_LDA(At, 0, 1); PG8_STAGE(PG8_SB(0, 0), b2, voffB); PG8_STAGE(PG8_SB(0, 1), b2 + hstep, voffB); PG8_STAGE(PG8_SA(0, 0), a2, voffA);
;             PG8_WAIT_V(8); PG8_WAIT_L(0); PG8_BAR; PG8_MMA(1, 0, At, B0); PG8_MMA(1, 1, At, B1); PG8_BAR; PG8_SCHED;
.LBB0_80:
	s_add_u32 s8, s0, 0x100
	s_addc_u32 s9, s1, 0
	s_add_i32 vcc_hi, 0, 0x10000
	s_cmp_eq_u32 vcc_lo, 12
	s_cselect_b32 s13, s66, s9
	s_cselect_b32 s12, s67, s8
	s_cselect_b32 s7, s82, s97
	s_cselect_b32 s6, s83, s96
	s_add_i32 s4, 0, 0x14000
	v_add_u32_e32 v38, vcc_hi, v242
	v_add_u32_e32 v158, s4, v242
	ds_read_b128 v[18:21], v38
	ds_read_b128 v[22:25], v38 offset:1024
	ds_read_b128 v[34:37], v38 offset:2048
	ds_read_b128 v[38:41], v38 offset:3072
	ds_read_b128 v[130:133], v158
	ds_read_b128 v[134:137], v158 offset:1024
	ds_read_b128 v[154:157], v158 offset:2048
	ds_read_b128 v[158:161], v158 offset:3072
	s_add_i32 m0, s11, 0xc000
	ds_read_b128 v[162:165], v243
	ds_read_b128 v[166:169], v243 offset:1024
	ds_read_b128 v[170:173], v243 offset:2048
	ds_read_b128 v[174:177], v243 offset:3072
	ds_read_b128 v[178:181], v243 offset:4096
	ds_read_b128 v[182:185], v243 offset:5120
	ds_read_b128 v[186:189], v243 offset:6144
	ds_read_b128 v[190:193], v243 offset:7168
	global_load_lds_dwordx4 v216, s[0:1]
	s_add_i32 m0, s11, 0xe000
	s_nop 0
	global_load_lds_dwordx4 v218, s[0:1]
	s_waitcnt vmcnt(8)
	s_waitcnt lgkmcnt(0)
	s_barrier
	s_waitcnt lgkmcnt(0)
	v_mfma_i32_16x16x64_i8 v[150:153], v[18:21], v[162:165], v[150:153]
	v_mfma_i32_16x16x64_i8 v[150:153], v[22:25], v[166:169], v[150:153]
	v_mfma_i32_16x16x64_i8 v[146:149], v[38:41], v[166:169], v[146:149]
	v_mfma_i32_16x16x64_i8 v[146:149], v[34:37], v[162:165], v[146:149]
	v_mfma_i32_16x16x64_i8 v[110:113], v[34:37], v[170:173], v[110:113]
	v_mfma_i32_16x16x64_i8 v[110:113], v[38:41], v[174:177], v[110:113]
	v_mfma_i32_16x16x64_i8 v[118:121], v[22:25], v[174:177], v[118:121]
	v_mfma_i32_16x16x64_i8 v[118:121], v[18:21], v[170:173], v[118:121]
	v_mfma_i32_16x16x64_i8 v[54:57], v[18:21], v[178:181], v[54:57]
	v_mfma_i32_16x16x64_i8 v[54:57], v[22:25], v[182:185], v[54:57]
	v_mfma_i32_16x16x64_i8 v[30:33], v[38:41], v[182:185], v[30:33]
	v_mfma_i32_16x16x64_i8 v[30:33], v[34:37], v[178:181], v[30:33]
	v_mfma_i32_16x16x64_i8 v[58:61], v[34:37], v[186:189], v[58:61]
	v_mfma_i32_16x16x64_i8 v[58:61], v[38:41], v[190:193], v[58:61]
	v_mfma_i32_16x16x64_i8 v[94:97], v[22:25], v[190:193], v[94:97]
	v_mfma_i32_16x16x64_i8 v[94:97], v[18:21], v[186:189], v[94:97]
	v_mfma_i32_16x16x64_i8 v[62:65], v[154:157], v[186:189], v[62:65]
	v_mfma_i32_16x16x64_i8 v[62:65], v[158:161], v[190:193], v[62:65]
	v_mfma_i32_16x16x64_i8 v[138:141], v[158:161], v[166:169], v[138:141]
	v_mfma_i32_16x16x64_i8 v[138:141], v[154:157], v[162:165], v[138:141]
	v_mfma_i32_16x16x64_i8 v[142:145], v[130:133], v[162:165], v[142:145]
	v_mfma_i32_16x16x64_i8 v[142:145], v[134:137], v[166:169], v[142:145]
	v_mfma_i32_16x16x64_i8 v[102:105], v[134:137], v[174:177], v[102:105]
	v_mfma_i32_16x16x64_i8 v[102:105], v[130:133], v[170:173], v[102:105]
	v_mfma_i32_16x16x64_i8 v[98:101], v[154:157], v[170:173], v[98:101]
	v_mfma_i32_16x16x64_i8 v[98:101], v[158:161], v[174:177], v[98:101]
	v_mfma_i32_16x16x64_i8 v[26:29], v[158:161], v[182:185], v[26:29]
	v_mfma_i32_16x16x64_i8 v[26:29], v[154:157], v[178:181], v[26:29]
	v_mfma_i32_16x16x64_i8 v[42:45], v[130:133], v[178:181], v[42:45]
	v_mfma_i32_16x16x64_i8 v[42:45], v[134:137], v[182:185], v[42:45]
	v_mfma_i32_16x16x64_i8 v[78:81], v[134:137], v[190:193], v[78:81]
	v_mfma_i32_16x16x64_i8 v[78:81], v[130:133], v[186:189], v[78:81]
	s_barrier
	s_add_i32 s0, vcc_hi, s69
	v_lshl_add_u64 v[198:199], s[6:7], 0, v[0:1]
	s_mov_b32 m0, s0
	ds_read_b128 v[162:165], v243 offset:16384
	ds_read_b128 v[166:169], v243 offset:17408
	ds_read_b128 v[170:173], v243 offset:18432
	ds_read_b128 v[174:177], v243 offset:19456
	ds_read_b128 v[178:181], v243 offset:20480
	ds_read_b128 v[182:185], v243 offset:21504
	ds_read_b128 v[186:189], v243 offset:22528
	ds_read_b128 v[190:193], v243 offset:23552
	global_load_lds_dwordx4 v[198:199], off
	s_add_i32 m0, s0, 0x2000
	s_add_u32 s0, s6, 0x40000
	v_lshl_add_u64 v[200:201], s[6:7], 0, v[214:215]
	s_addc_u32 s1, s7, 0
	s_add_i32 s4, s4, s69
	global_load_lds_dwordx4 v[200:201], off
	s_mov_b32 m0, s4
	v_lshl_add_u64 v[206:207], s[12:13], 0, v[210:211]
	global_load_lds_dwordx4 v0, s[0:1]
	s_add_i32 m0, s4, 0x2000
	v_lshl_add_u64 v[220:221], s[12:13], 0, v[212:213]
	global_load_lds_dwordx4 v214, s[0:1]
	s_mov_b32 m0, s11
	s_nop 0
	global_load_lds_dwordx4 v[206:207], off
	s_mov_b32 m0, s71
	s_nop 0
	global_load_lds_dwordx4 v[220:221], off
	s_waitcnt vmcnt(8)
	s_waitcnt lgkmcnt(0)
	s_barrier
	s_waitcnt lgkmcnt(0)
	v_mfma_i32_16x16x64_i8 v[106:109], v[18:21], v[162:165], v[106:109]
	v_mfma_i32_16x16x64_i8 v[106:109], v[22:25], v[166:169], v[106:109]
	v_mfma_i32_16x16x64_i8 v[46:49], v[34:37], v[162:165], v[46:49]
	v_mfma_i32_16x16x64_i8 v[46:49], v[38:41], v[166:169], v[46:49]
	v_mfma_i32_16x16x64_i8 v[6:9], v[34:37], v[170:173], v[6:9]
	v_mfma_i32_16x16x64_i8 v[6:9], v[38:41], v[174:177], v[6:9]
	v_mfma_i32_16x16x64_i8 v[14:17], v[18:21], v[170:173], v[14:17]
	v_mfma_i32_16x16x64_i8 v[14:17], v[22:25], v[174:177], v[14:17]
	v_mfma_i32_16x16x64_i8 v[90:93], v[18:21], v[178:181], v[90:93]
	v_mfma_i32_16x16x64_i8 v[90:93], v[22:25], v[182:185], v[90:93]
	v_mfma_i32_16x16x64_i8 v[86:89], v[34:37], v[178:181], v[86:89]
	v_mfma_i32_16x16x64_i8 v[86:89], v[38:41], v[182:185], v[86:89]
	v_mfma_i32_16x16x64_i8 v[18:21], v[18:21], v[186:189], v[126:129]
	v_mfma_i32_16x16x64_i8 v[18:21], v[22:25], v[190:193], v[18:21]
	v_mfma_i32_16x16x64_i8 v[22:25], v[34:37], v[186:189], v[66:69]
	v_mfma_i32_16x16x64_i8 v[22:25], v[38:41], v[190:193], v[22:25]
	v_mfma_i32_16x16x64_i8 v[38:41], v[154:157], v[162:165], v[50:53]
	v_mfma_i32_16x16x64_i8 v[38:41], v[158:161], v[166:169], v[38:41]
	v_mfma_i32_16x16x64_i8 v[2:5], v[154:157], v[170:173], v[2:5]
	v_mfma_i32_16x16x64_i8 v[2:5], v[158:161], v[174:177], v[2:5]
	v_mfma_i32_16x16x64_i8 v[10:13], v[130:133], v[170:173], v[10:13]
	v_mfma_i32_16x16x64_i8 v[10:13], v[134:137], v[174:177], v[10:13]
	v_mfma_i32_16x16x64_i8 v[50:53], v[130:133], v[178:181], v[82:85]
	v_mfma_i32_16x16x64_i8 v[82:85], v[134:137], v[182:185], v[50:53]
	v_mfma_i32_16x16x64_i8 v[34:37], v[130:133], v[162:165], v[114:117]
	v_mfma_i32_16x16x64_i8 v[34:37], v[134:137], v[166:169], v[34:37]
	v_mfma_i32_16x16x64_i8 v[50:53], v[154:157], v[178:181], v[74:77]
	v_mfma_i32_16x16x64_i8 v[74:77], v[158:161], v[182:185], v[50:53]
	v_mfma_i32_16x16x64_i8 v[50:53], v[130:133], v[186:189], v[122:125]
	v_mfma_i32_16x16x64_i8 v[122:125], v[134:137], v[190:193], v[50:53]
	v_mfma_i32_16x16x64_i8 v[50:53], v[154:157], v[186:189], v[70:73]
	v_mfma_i32_16x16x64_i8 v[70:73], v[158:161], v[190:193], v[50:53]
	s_barrier
; #define PG8_STAGE(bufoff, gbase, voff) do { _Pragma("unroll") for (int _i = 0; _i < 2; ++_i) \
;         __builtin_amdgcn_global_load_lds((const unsigned*)((const char*)(gbase) + (voff)[_i]), (PG8_LAS unsigned*)(lds + (bufoff) + ldsw + _i * 8192), 16, 0, 0); } while (0)
; #define PG8_LDA(dst, b, h) do { _Pragma("unroll") for (int m = 0; m < 4; ++m) _Pragma("unroll") for (int k = 0; k < 2; ++k) dst[m][k] = *(const PG8_LAS bf16x8*)(lds + PG8_SA(b, h) + aoff + m * 2048 + k * 1024); } while (0)
; #define PG8_LDB(dst, b, h) do { _Pragma("unroll") for (int n = 0; n < 2; ++n) _Pragma("unroll") for (int k = 0; k < 2; ++k) dst[n][k] = *(const PG8_LAS bf16x8*)(lds + PG8_SB(b, h) + boff + n * 2048 + k * 1024); } while (0)
; #define PG8_MMA(ai, bj, At, Bt) do { __builtin_amdgcn_s_setprio(1); _Pragma("unroll") for (int m = 0; m < 4; ++m) _Pragma("unroll") for (int n = 0; n < 2; ++n) _Pragma("unroll") for (int k = 0; k < 2; ++k) \
;         acc[ai][bj][m][n] = mma16<Epi::I8>(Bt[n][k], At[m][k], acc[ai][bj][m][n]); __builtin_amdgcn_s_setprio(0); } while (0)
; #define PG8_WAIT_V(n) asm volatile("s_waitcnt vmcnt(" #n ")" ::: "memory")
; #define PG8_WAIT_L(n) asm volatile("s_waitcnt lgkmcnt(" #n ")" ::: "memory")
; #define PG8_BAR __builtin_amdgcn_s_barrier()
; #define PG8_SCHED __builtin_amdgcn_sched_barrier(0)
; template <class Epi, class Sched, bool ALIGN_EPI = false, bool SP2 = false>
; __device__ __forceinline__ void gemm_phase(PG8_LAS unsigned char* lds, const Gemm g, const Sched& S, const Epi& E) {
;     ...
;             PG8_LDB(B0, 1, 0); PG8_LDB(B1, 1, 1); PG8_SCHED; PG8_LDA(At, 1, 0); PG8_STAGE(PG8_SA(0, 1), a2 + hstep, voffA);
;             PG8_WAIT_V(8); PG8_WAIT_L(0); PG8_BAR; PG8_MMA(0, 0, At, B0); PG8_MMA(0, 1, At, B1); PG8_BAR; PG8_SCHED;
;             PG8_LDA(At, 1, 1); PG8_STAGE(PG8_SB(1, 0), b3, voffB); PG8_STAGE(PG8_SB(1, 1), b3 + hstep, voffB); PG8_STAGE(PG8_SA(1, 0), a3, voffA);
;             PG8_WAIT_V(8); PG8_WAIT_L(0); PG8_BAR; PG8_MMA(1, 0, At, B0); PG8_MMA(1, 1, At, B1); PG8_BAR; PG8_SCHED;
	s_add_i32 s4, 0, 0x18000
	v_add_u32_e32 v126, s4, v242
	s_add_i32 s5, 0, 0x1c000
	ds_read_b128 v[50:53], v126
	ds_read_b128 v[66:69], v126 offset:1024
	ds_read_b128 v[114:117], v126 offset:2048
	ds_read_b128 v[130:133], v126 offset:3072
	v_add_u32_e32 v126, s5, v242
	ds_read_b128 v[134:137], v126
	ds_read_b128 v[154:157], v126 offset:1024
	ds_read_b128 v[158:161], v126 offset:2048
	ds_read_b128 v[162:165], v126 offset:3072
	s_add_u32 s0, s12, 0x40000
	s_addc_u32 s1, s13, 0
	s_mov_b32 m0, s80
	ds_read_b128 v[126:129], v243 offset:32768
	ds_read_b128 v[166:169], v243 offset:33792
	ds_read_b128 v[170:173], v243 offset:34816
	ds_read_b128 v[174:177], v243 offset:35840
	ds_read_b128 v[178:181], v243 offset:36864
	ds_read_b128 v[182:185], v243 offset:37888
	ds_read_b128 v[186:189], v243 offset:38912
	ds_read_b128 v[190:193], v243 offset:39936
	global_load_lds_dwordx4 v210, s[0:1]
	s_mov_b32 m0, s81
	s_nop 0
	global_load_lds_dwordx4 v212, s[0:1]
	s_waitcnt vmcnt(8)
	s_waitcnt lgkmcnt(0)
	s_barrier
	s_waitcnt lgkmcnt(0)
	v_mfma_i32_16x16x64_i8 v[150:153], v[50:53], v[126:129], v[150:153]
	v_mfma_i32_16x16x64_i8 v[150:153], v[66:69], v[166:169], v[150:153]
	v_mfma_i32_16x16x64_i8 v[146:149], v[114:117], v[126:129], v[146:149]
	v_mfma_i32_16x16x64_i8 v[146:149], v[130:133], v[166:169], v[146:149]
	v_mfma_i32_16x16x64_i8 v[110:113], v[114:117], v[170:173], v[110:113]
	v_mfma_i32_16x16x64_i8 v[110:113], v[130:133], v[174:177], v[110:113]
	v_mfma_i32_16x16x64_i8 v[118:121], v[50:53], v[170:173], v[118:121]
	v_mfma_i32_16x16x64_i8 v[118:121], v[66:69], v[174:177], v[118:121]
	v_mfma_i32_16x16x64_i8 v[54:57], v[50:53], v[178:181], v[54:57]
	v_mfma_i32_16x16x64_i8 v[54:57], v[66:69], v[182:185], v[54:57]
	v_mfma_i32_16x16x64_i8 v[30:33], v[114:117], v[178:181], v[30:33]
	v_mfma_i32_16x16x64_i8 v[30:33], v[130:133], v[182:185], v[30:33]
	v_mfma_i32_16x16x64_i8 v[58:61], v[114:117], v[186:189], v[58:61]
	v_mfma_i32_16x16x64_i8 v[58:61], v[130:133], v[190:193], v[58:61]
	v_mfma_i32_16x16x64_i8 v[94:97], v[50:53], v[186:189], v[94:97]
	v_mfma_i32_16x16x64_i8 v[94:97], v[66:69], v[190:193], v[94:97]
	v_mfma_i32_16x16x64_i8 v[142:145], v[134:137], v[126:129], v[142:145]
	v_mfma_i32_16x16x64_i8 v[142:145], v[154:157], v[166:169], v[142:145]
	v_mfma_i32_16x16x64_i8 v[126:129], v[158:161], v[126:129], v[138:141]
	v_mfma_i32_16x16x64_i8 v[138:141], v[162:165], v[166:169], v[126:129]
	v_mfma_i32_16x16x64_i8 v[98:101], v[158:161], v[170:173], v[98:101]
	v_mfma_i32_16x16x64_i8 v[98:101], v[162:165], v[174:177], v[98:101]
	v_mfma_i32_16x16x64_i8 v[102:105], v[134:137], v[170:173], v[102:105]
	v_mfma_i32_16x16x64_i8 v[102:105], v[154:157], v[174:177], v[102:105]
	v_mfma_i32_16x16x64_i8 v[42:45], v[134:137], v[178:181], v[42:45]
	v_mfma_i32_16x16x64_i8 v[42:45], v[154:157], v[182:185], v[42:45]
	v_mfma_i32_16x16x64_i8 v[26:29], v[158:161], v[178:181], v[26:29]
	v_mfma_i32_16x16x64_i8 v[26:29], v[162:165], v[182:185], v[26:29]
	v_mfma_i32_16x16x64_i8 v[62:65], v[158:161], v[186:189], v[62:65]
	v_mfma_i32_16x16x64_i8 v[62:65], v[162:165], v[190:193], v[62:65]
	v_mfma_i32_16x16x64_i8 v[78:81], v[134:137], v[186:189], v[78:81]
	v_mfma_i32_16x16x64_i8 v[78:81], v[154:157], v[190:193], v[78:81]
	s_barrier
	s_add_i32 s0, s4, s69
	v_lshl_add_u64 v[126:127], v[198:199], 0, s[92:93]
	s_mov_b32 m0, s0
	ds_read_b128 v[166:169], v243 offset:49152
	ds_read_b128 v[170:173], v243 offset:50176
	ds_read_b128 v[174:177], v243 offset:51200
	ds_read_b128 v[178:181], v243 offset:52224
	ds_read_b128 v[182:185], v243 offset:53248
	ds_read_b128 v[186:189], v243 offset:54272
	ds_read_b128 v[190:193], v243 offset:55296
	ds_read_b128 v[194:197], v243 offset:56320
	global_load_lds_dwordx4 v[126:127], off
	s_add_i32 m0, s0, 0x2000
	s_add_u32 s0, s6, 0x40080
	v_lshl_add_u64 v[126:127], v[200:201], 0, s[92:93]
	s_addc_u32 s1, s7, 0
	s_add_i32 s4, s5, s69
	global_load_lds_dwordx4 v[126:127], off
	s_mov_b32 m0, s4
	s_nop 0
	global_load_lds_dwordx4 v0, s[0:1]
	s_add_i32 m0, s4, 0x2000
	s_nop 0
	global_load_lds_dwordx4 v214, s[0:1]
	v_lshl_add_u64 v[126:127], v[206:207], 0, s[92:93]
	s_mov_b32 m0, s84
	s_nop 0
	global_load_lds_dwordx4 v[126:127], off
	v_lshl_add_u64 v[126:127], v[220:221], 0, s[92:93]
	s_mov_b32 m0, s85
	s_nop 0
	global_load_lds_dwordx4 v[126:127], off
	s_waitcnt vmcnt(8)
	s_waitcnt lgkmcnt(0)
	s_barrier
	s_waitcnt lgkmcnt(0)
	v_mfma_i32_16x16x64_i8 v[18:21], v[50:53], v[190:193], v[18:21]
	v_mfma_i32_16x16x64_i8 v[126:129], v[66:69], v[194:197], v[18:21]
	v_mfma_i32_16x16x64_i8 v[106:109], v[50:53], v[166:169], v[106:109]
	v_mfma_i32_16x16x64_i8 v[106:109], v[66:69], v[170:173], v[106:109]
	v_mfma_i32_16x16x64_i8 v[46:49], v[114:117], v[166:169], v[46:49]
	v_mfma_i32_16x16x64_i8 v[46:49], v[130:133], v[170:173], v[46:49]
	v_mfma_i32_16x16x64_i8 v[6:9], v[114:117], v[174:177], v[6:9]
	v_mfma_i32_16x16x64_i8 v[6:9], v[130:133], v[178:181], v[6:9]
	v_mfma_i32_16x16x64_i8 v[14:17], v[50:53], v[174:177], v[14:17]
	v_mfma_i32_16x16x64_i8 v[14:17], v[66:69], v[178:181], v[14:17]
	v_mfma_i32_16x16x64_i8 v[90:93], v[50:53], v[182:185], v[90:93]
	v_mfma_i32_16x16x64_i8 v[90:93], v[66:69], v[186:189], v[90:93]
	v_mfma_i32_16x16x64_i8 v[86:89], v[114:117], v[182:185], v[86:89]
	v_mfma_i32_16x16x64_i8 v[86:89], v[130:133], v[186:189], v[86:89]
	v_mfma_i32_16x16x64_i8 v[18:21], v[114:117], v[190:193], v[22:25]
	v_mfma_i32_16x16x64_i8 v[66:69], v[130:133], v[194:197], v[18:21]
	v_mfma_i32_16x16x64_i8 v[18:21], v[134:137], v[166:169], v[34:37]
	v_mfma_i32_16x16x64_i8 v[114:117], v[154:157], v[170:173], v[18:21]
	v_mfma_i32_16x16x64_i8 v[10:13], v[134:137], v[174:177], v[10:13]
	v_mfma_i32_16x16x64_i8 v[10:13], v[154:157], v[178:181], v[10:13]
	v_mfma_i32_16x16x64_i8 v[2:5], v[158:161], v[174:177], v[2:5]
	v_mfma_i32_16x16x64_i8 v[2:5], v[162:165], v[178:181], v[2:5]
	v_mfma_i32_16x16x64_i8 v[18:21], v[158:161], v[166:169], v[38:41]
	v_mfma_i32_16x16x64_i8 v[50:53], v[162:165], v[170:173], v[18:21]
	v_mfma_i32_16x16x64_i8 v[18:21], v[134:137], v[182:185], v[82:85]
	v_mfma_i32_16x16x64_i8 v[82:85], v[154:157], v[186:189], v[18:21]
	v_mfma_i32_16x16x64_i8 v[18:21], v[158:161], v[182:185], v[74:77]
	v_mfma_i32_16x16x64_i8 v[74:77], v[162:165], v[186:189], v[18:21]
	v_mfma_i32_16x16x64_i8 v[18:21], v[134:137], v[190:193], v[122:125]
	v_mfma_i32_16x16x64_i8 v[122:125], v[154:157], v[194:197], v[18:21]
	v_mfma_i32_16x16x64_i8 v[18:21], v[158:161], v[190:193], v[70:73]
	v_mfma_i32_16x16x64_i8 v[70:73], v[162:165], v[194:197], v[18:21]
	s_barrier
	s_add_i32 vcc_lo, vcc_lo, 2
	s_add_u32 s96, s96, 0x100
	s_addc_u32 s97, s97, 0
	s_cmp_gt_u32 vcc_lo, 13
	s_mov_b64 s[0:1], s[8:9]
	s_cbranch_scc0 .LBB0_80

; #define PG8_STAGE(bufoff, gbase, voff) do { _Pragma("unroll") for (int _i = 0; _i < 2; ++_i) \
;         __builtin_amdgcn_global_load_lds((const unsigned*)((const char*)(gbase) + (voff)[_i]), (PG8_LAS unsigned*)(lds + (bufoff) + ldsw + _i * 8192), 16, 0, 0); } while (0)
; #define PG8_LDA(dst, b, h) do { _Pragma("unroll") for (int m = 0; m < 4; ++m) _Pragma("unroll") for (int k = 0; k < 2; ++k) dst[m][k] = *(const PG8_LAS bf16x8*)(lds + PG8_SA(b, h) + aoff + m * 2048 + k * 1024); } while (0)
; #define PG8_LDB(dst, b, h) do { _Pragma("unroll") for (int n = 0; n < 2; ++n) _Pragma("unroll") for (int k = 0; k < 2; ++k) dst[n][k] = *(const PG8_LAS bf16x8*)(lds + PG8_SB(b, h) + boff + n * 2048 + k * 1024); } while (0)
; #define PG8_MMA(ai, bj, At, Bt) do { __builtin_amdgcn_s_setprio(1); _Pragma("unroll") for (int m = 0; m < 4; ++m) _Pragma("unroll") for (int n = 0; n < 2; ++n) _Pragma("unroll") for (int k = 0; k < 2; ++k) \
;         acc[ai][bj][m][n] = mma16<Epi::I8>(Bt[n][k], At[m][k], acc[ai][bj][m][n]); __builtin_amdgcn_s_setprio(0); } while (0)
; #define PG8_WAIT_V(n) asm volatile("s_waitcnt vmcnt(" #n ")" ::: "memory")
; #define PG8_WAIT_L(n) asm volatile("s_waitcnt lgkmcnt(" #n ")" ::: "memory")
; template <class Epi, class Sched, bool ALIGN_EPI = false, bool SP2 = false>
; __device__ __forceinline__ void gemm_phase(PG8_LAS unsigned char* lds, const Gemm g, const Sched& S, const Epi& E) {
;     ...
;         for (int t = 0; t < nt; t += 2) {
;             const bool last = (t == nt - 2);
;             const char* a1 = cA + (size_t)(t + 1) * kstep;
;             const char* a2 = last ? nA : cA + (size_t)(t + 2) * kstep; const char* b2 = last ? nB : cB + (size_t)(t + 2) * kstep;
;             const char* a3 = a2 + kstep; const char* b3 = b2 + kstep;
;             if (last && has_next) S.a_ready(nxt);
;             if constexpr (SP2) {
;             PG8_LDB(B0, 0, 0); PG8_LDB(B1, 0, 1); PG8_SCHED; PG8_LDA(At, 0, 0); PG8_STAGE(PG8_SA(1, 1), a1 + hstep, voffA);
;             PG8_WAIT_V(8); PG8_WAIT_L(0); PG8_BAR; PG8_MMA(0, 0, At, B0); PG8_MMA(0, 1, At, B1); PG8_BAR; PG8_SCHED;
;             PG8_LDA(At, 0, 1); PG8_STAGE(PG8_SB(0, 0), b2, voffB); PG8_STAGE(PG8_SB(0, 1), b2 + hstep, voffB); PG8_STAGE(PG8_SA(0, 0), a2, voffA);
;             PG8_WAIT_V(8); PG8_WAIT_L(0); PG8_BAR; PG8_MMA(1, 0, At, B0); PG8_MMA(1, 1, At, B1); PG8_BAR; PG8_SCHED;
.Lpeel291:
	s_add_u32 s84, s8, 0x100
	s_addc_u32 s85, s9, 0
	s_add_i32 s66, 0, 0x10000
	s_cmp_eq_u32 s10, 12
	s_cselect_b32 vcc_hi, s5, s85
	s_cselect_b32 vcc_lo, s7, s84
	s_cselect_b32 s97, s11, s68
	s_cselect_b32 s96, s67, s69
	s_add_i32 s70, 0, 0x14000
	v_add_u32_e32 v110, s66, v175
	v_add_u32_e32 v168, s70, v175
	s_waitcnt vmcnt(0)
	ds_read_b128 v[66:69], v110
	ds_read_b128 v[70:73], v110 offset:1024
	ds_read_b128 v[106:109], v110 offset:2048
	ds_read_b128 v[110:113], v110 offset:3072
	ds_read_b128 v[114:117], v168
	ds_read_b128 v[118:121], v168 offset:1024
	ds_read_b128 v[126:129], v168 offset:2048
	ds_read_b128 v[178:181], v168 offset:3072
	v_lshl_add_u64 v[168:169], s[8:9], 0, v[164:165]
	s_add_i32 m0, s1, 0xc000
	ds_read_b128 v[182:185], v177
	ds_read_b128 v[186:189], v177 offset:1024
	ds_read_b128 v[190:193], v177 offset:2048
	ds_read_b128 v[194:197], v177 offset:3072
	ds_read_b128 v[198:201], v177 offset:4096
	ds_read_b128 v[210:213], v177 offset:5120
	ds_read_b128 v[214:217], v177 offset:6144
	ds_read_b128 v[218:221], v177 offset:7168
	global_load_lds_dwordx4 v[168:169], off
	v_lshl_add_u64 v[168:169], s[8:9], 0, v[166:167]
	s_add_i32 m0, s1, 0xe000
	s_nop 0
	global_load_lds_dwordx4 v[168:169], off
	s_waitcnt vmcnt(8)
	s_waitcnt lgkmcnt(0)
	s_barrier
	s_waitcnt lgkmcnt(0)
	v_mfma_i32_16x16x64_i8 v[154:157], v[66:69], v[182:185], 0
	v_mfma_i32_16x16x64_i8 v[154:157], v[70:73], v[186:189], v[154:157]
	v_mfma_i32_16x16x64_i8 v[146:149], v[110:113], v[186:189], 0
	v_mfma_i32_16x16x64_i8 v[146:149], v[106:109], v[182:185], v[146:149]
	v_mfma_i32_16x16x64_i8 v[138:141], v[106:109], v[190:193], 0
	v_mfma_i32_16x16x64_i8 v[138:141], v[110:113], v[194:197], v[138:141]
	v_mfma_i32_16x16x64_i8 v[150:153], v[70:73], v[194:197], 0
	v_mfma_i32_16x16x64_i8 v[150:153], v[66:69], v[190:193], v[150:153]
	v_mfma_i32_16x16x64_i8 v[142:145], v[66:69], v[198:201], 0
	v_mfma_i32_16x16x64_i8 v[142:145], v[70:73], v[210:213], v[142:145]
	v_mfma_i32_16x16x64_i8 v[130:133], v[110:113], v[210:213], 0
	v_mfma_i32_16x16x64_i8 v[130:133], v[106:109], v[198:201], v[130:133]
	v_mfma_i32_16x16x64_i8 v[122:125], v[106:109], v[214:217], 0
	v_mfma_i32_16x16x64_i8 v[122:125], v[110:113], v[218:221], v[122:125]
	v_mfma_i32_16x16x64_i8 v[134:137], v[70:73], v[218:221], 0
	v_mfma_i32_16x16x64_i8 v[134:137], v[66:69], v[214:217], v[134:137]
	v_mfma_i32_16x16x64_i8 v[74:77], v[126:129], v[214:217], 0
	v_mfma_i32_16x16x64_i8 v[74:77], v[178:181], v[218:221], v[74:77]
	v_mfma_i32_16x16x64_i8 v[94:97], v[178:181], v[186:189], 0
	v_mfma_i32_16x16x64_i8 v[94:97], v[126:129], v[182:185], v[94:97]
	v_mfma_i32_16x16x64_i8 v[102:105], v[114:117], v[182:185], 0
	v_mfma_i32_16x16x64_i8 v[102:105], v[118:121], v[186:189], v[102:105]
	v_mfma_i32_16x16x64_i8 v[98:101], v[118:121], v[194:197], 0
	v_mfma_i32_16x16x64_i8 v[98:101], v[114:117], v[190:193], v[98:101]
	v_mfma_i32_16x16x64_i8 v[86:89], v[126:129], v[190:193], 0
	v_mfma_i32_16x16x64_i8 v[86:89], v[178:181], v[194:197], v[86:89]
	v_mfma_i32_16x16x64_i8 v[78:81], v[178:181], v[210:213], 0
	v_mfma_i32_16x16x64_i8 v[78:81], v[126:129], v[198:201], v[78:81]
	v_mfma_i32_16x16x64_i8 v[90:93], v[114:117], v[198:201], 0
	v_mfma_i32_16x16x64_i8 v[90:93], v[118:121], v[210:213], v[90:93]
	v_mfma_i32_16x16x64_i8 v[82:85], v[118:121], v[218:221], 0
	v_mfma_i32_16x16x64_i8 v[82:85], v[114:117], v[214:217], v[82:85]
	s_barrier
	s_add_i32 s8, s66, s81
	v_lshl_add_u64 v[168:169], s[96:97], 0, v[0:1]
	s_mov_b32 m0, s8
	ds_read_b128 v[182:185], v177 offset:16384
	ds_read_b128 v[186:189], v177 offset:17408
	ds_read_b128 v[190:193], v177 offset:18432
	ds_read_b128 v[194:197], v177 offset:19456
	ds_read_b128 v[198:201], v177 offset:20480
	ds_read_b128 v[210:213], v177 offset:21504
	ds_read_b128 v[214:217], v177 offset:22528
	ds_read_b128 v[218:221], v177 offset:23552
	global_load_lds_dwordx4 v[168:169], off
	s_add_i32 m0, s8, 0x2000
	s_add_u32 s8, s96, 0x40000
	v_lshl_add_u64 v[206:207], s[96:97], 0, v[158:159]
	s_addc_u32 s9, s97, 0
	s_add_i32 s66, s70, s81
	global_load_lds_dwordx4 v[206:207], off
	v_lshl_add_u64 v[222:223], s[8:9], 0, v[0:1]
	s_mov_b32 m0, s66
	v_lshl_add_u64 v[224:225], vcc, 0, v[160:161]
	global_load_lds_dwordx4 v[222:223], off
	v_lshl_add_u64 v[222:223], s[8:9], 0, v[158:159]
	s_add_i32 m0, s66, 0x2000
	s_nop 0
	global_load_lds_dwordx4 v[222:223], off
	v_lshl_add_u64 v[222:223], vcc, 0, v[162:163]
	s_mov_b32 m0, s1
	s_nop 0
	global_load_lds_dwordx4 v[222:223], off
	s_mov_b32 m0, s58
	s_nop 0
	global_load_lds_dwordx4 v[224:225], off
	s_waitcnt vmcnt(8)
	s_waitcnt lgkmcnt(0)
	s_barrier
	s_waitcnt lgkmcnt(0)
	v_mfma_i32_16x16x64_i8 v[62:65], v[66:69], v[182:185], 0
	v_mfma_i32_16x16x64_i8 v[62:65], v[70:73], v[186:189], v[62:65]
	v_mfma_i32_16x16x64_i8 v[54:57], v[110:113], v[186:189], 0
	v_mfma_i32_16x16x64_i8 v[54:57], v[106:109], v[182:185], v[54:57]
	v_mfma_i32_16x16x64_i8 v[46:49], v[106:109], v[190:193], 0
	v_mfma_i32_16x16x64_i8 v[46:49], v[110:113], v[194:197], v[46:49]
	v_mfma_i32_16x16x64_i8 v[58:61], v[70:73], v[194:197], 0
	v_mfma_i32_16x16x64_i8 v[58:61], v[66:69], v[190:193], v[58:61]
	v_mfma_i32_16x16x64_i8 v[50:53], v[66:69], v[198:201], 0
	v_mfma_i32_16x16x64_i8 v[50:53], v[70:73], v[210:213], v[50:53]
	v_mfma_i32_16x16x64_i8 v[38:41], v[110:113], v[210:213], 0
	v_mfma_i32_16x16x64_i8 v[38:41], v[106:109], v[198:201], v[38:41]
	v_mfma_i32_16x16x64_i8 v[34:37], v[106:109], v[214:217], 0
	v_mfma_i32_16x16x64_i8 v[34:37], v[110:113], v[218:221], v[34:37]
	v_mfma_i32_16x16x64_i8 v[42:45], v[70:73], v[218:221], 0
	v_mfma_i32_16x16x64_i8 v[42:45], v[66:69], v[214:217], v[42:45]
	v_mfma_i32_16x16x64_i8 v[2:5], v[126:129], v[214:217], 0
	v_mfma_i32_16x16x64_i8 v[2:5], v[178:181], v[218:221], v[2:5]
	v_mfma_i32_16x16x64_i8 v[22:25], v[178:181], v[186:189], 0
	v_mfma_i32_16x16x64_i8 v[22:25], v[126:129], v[182:185], v[22:25]
	v_mfma_i32_16x16x64_i8 v[30:33], v[114:117], v[182:185], 0
	v_mfma_i32_16x16x64_i8 v[30:33], v[118:121], v[186:189], v[30:33]
	v_mfma_i32_16x16x64_i8 v[26:29], v[118:121], v[194:197], 0
	v_mfma_i32_16x16x64_i8 v[26:29], v[114:117], v[190:193], v[26:29]
	v_mfma_i32_16x16x64_i8 v[14:17], v[126:129], v[190:193], 0
	v_mfma_i32_16x16x64_i8 v[14:17], v[178:181], v[194:197], v[14:17]
	v_mfma_i32_16x16x64_i8 v[6:9], v[178:181], v[210:213], 0
	v_mfma_i32_16x16x64_i8 v[6:9], v[126:129], v[198:201], v[6:9]
	v_mfma_i32_16x16x64_i8 v[18:21], v[114:117], v[198:201], 0
	v_mfma_i32_16x16x64_i8 v[18:21], v[118:121], v[210:213], v[18:21]
	v_mfma_i32_16x16x64_i8 v[10:13], v[118:121], v[218:221], 0
	v_mfma_i32_16x16x64_i8 v[10:13], v[114:117], v[214:217], v[10:13]
	s_barrier
; #define PG8_STAGE(bufoff, gbase, voff) do { _Pragma("unroll") for (int _i = 0; _i < 2; ++_i) \
;         __builtin_amdgcn_global_load_lds((const unsigned*)((const char*)(gbase) + (voff)[_i]), (PG8_LAS unsigned*)(lds + (bufoff) + ldsw + _i * 8192), 16, 0, 0); } while (0)
; #define PG8_LDA(dst, b, h) do { _Pragma("unroll") for (int m = 0; m < 4; ++m) _Pragma("unroll") for (int k = 0; k < 2; ++k) dst[m][k] = *(const PG8_LAS bf16x8*)(lds + PG8_SA(b, h) + aoff + m * 2048 + k * 1024); } while (0)
; #define PG8_LDB(dst, b, h) do { _Pragma("unroll") for (int n = 0; n < 2; ++n) _Pragma("unroll") for (int k = 0; k < 2; ++k) dst[n][k] = *(const PG8_LAS bf16x8*)(lds + PG8_SB(b, h) + boff + n * 2048 + k * 1024); } while (0)
; #define PG8_MMA(ai, bj, At, Bt) do { __builtin_amdgcn_s_setprio(1); _Pragma("unroll") for (int m = 0; m < 4; ++m) _Pragma("unroll") for (int n = 0; n < 2; ++n) _Pragma("unroll") for (int k = 0; k < 2; ++k) \
;         acc[ai][bj][m][n] = mma16<Epi::I8>(Bt[n][k], At[m][k], acc[ai][bj][m][n]); __builtin_amdgcn_s_setprio(0); } while (0)
; #define PG8_WAIT_V(n) asm volatile("s_waitcnt vmcnt(" #n ")" ::: "memory")
; #define PG8_WAIT_L(n) asm volatile("s_waitcnt lgkmcnt(" #n ")" ::: "memory")
; #define PG8_BAR __builtin_amdgcn_s_barrier()
; #define PG8_SCHED __builtin_amdgcn_sched_barrier(0)
; template <class Epi, class Sched, bool ALIGN_EPI = false, bool SP2 = false>
; __device__ __forceinline__ void gemm_phase(PG8_LAS unsigned char* lds, const Gemm g, const Sched& S, const Epi& E) {
;     ...
;             PG8_LDB(B0, 1, 0); PG8_LDB(B1, 1, 1); PG8_SCHED; PG8_LDA(At, 1, 0); PG8_STAGE(PG8_SA(0, 1), a2 + hstep, voffA);
;             PG8_WAIT_V(8); PG8_WAIT_L(0); PG8_BAR; PG8_MMA(0, 0, At, B0); PG8_MMA(0, 1, At, B1); PG8_BAR; PG8_SCHED;
;             PG8_LDA(At, 1, 1); PG8_STAGE(PG8_SB(1, 0), b3, voffB); PG8_STAGE(PG8_SB(1, 1), b3 + hstep, voffB); PG8_STAGE(PG8_SA(1, 0), a3, voffA);
;             PG8_WAIT_V(8); PG8_WAIT_L(0); PG8_BAR; PG8_MMA(1, 0, At, B0); PG8_MMA(1, 1, At, B1); PG8_BAR; PG8_SCHED;
	s_add_i32 s66, 0, 0x18000
	s_add_i32 s70, 0, 0x1c000
	v_add_u32_e32 v110, s66, v175
	v_add_u32_e32 v170, s70, v175
	ds_read_b128 v[66:69], v110
	ds_read_b128 v[70:73], v110 offset:1024
	ds_read_b128 v[106:109], v110 offset:2048
	ds_read_b128 v[110:113], v110 offset:3072
	ds_read_b128 v[114:117], v170
	ds_read_b128 v[118:121], v170 offset:1024
	ds_read_b128 v[126:129], v170 offset:2048
	ds_read_b128 v[178:181], v170 offset:3072
	s_add_u32 s8, vcc_lo, 0x40000
	s_addc_u32 s9, vcc_hi, 0
	s_mov_b32 m0, s80
	v_lshl_add_u64 v[226:227], s[8:9], 0, v[162:163]
	ds_read_b128 v[182:185], v177 offset:32768
	ds_read_b128 v[186:189], v177 offset:33792
	ds_read_b128 v[190:193], v177 offset:34816
	ds_read_b128 v[194:197], v177 offset:35840
	ds_read_b128 v[198:201], v177 offset:36864
	ds_read_b128 v[210:213], v177 offset:37888
	ds_read_b128 v[214:217], v177 offset:38912
	ds_read_b128 v[218:221], v177 offset:39936
	global_load_lds_dwordx4 v[226:227], off
	v_lshl_add_u64 v[226:227], s[8:9], 0, v[160:161]
	s_mov_b32 m0, s0
	s_nop 0
	global_load_lds_dwordx4 v[226:227], off
	s_waitcnt vmcnt(8)
	s_waitcnt lgkmcnt(0)
	s_barrier
	s_waitcnt lgkmcnt(0)
	v_mfma_i32_16x16x64_i8 v[154:157], v[66:69], v[182:185], v[154:157]
	v_mfma_i32_16x16x64_i8 v[154:157], v[70:73], v[186:189], v[154:157]
	v_mfma_i32_16x16x64_i8 v[146:149], v[110:113], v[186:189], v[146:149]
	v_mfma_i32_16x16x64_i8 v[146:149], v[106:109], v[182:185], v[146:149]
	v_mfma_i32_16x16x64_i8 v[138:141], v[106:109], v[190:193], v[138:141]
	v_mfma_i32_16x16x64_i8 v[138:141], v[110:113], v[194:197], v[138:141]
	v_mfma_i32_16x16x64_i8 v[150:153], v[70:73], v[194:197], v[150:153]
	v_mfma_i32_16x16x64_i8 v[150:153], v[66:69], v[190:193], v[150:153]
	v_mfma_i32_16x16x64_i8 v[142:145], v[66:69], v[198:201], v[142:145]
	v_mfma_i32_16x16x64_i8 v[142:145], v[70:73], v[210:213], v[142:145]
	v_mfma_i32_16x16x64_i8 v[130:133], v[110:113], v[210:213], v[130:133]
	v_mfma_i32_16x16x64_i8 v[130:133], v[106:109], v[198:201], v[130:133]
	v_mfma_i32_16x16x64_i8 v[122:125], v[106:109], v[214:217], v[122:125]
	v_mfma_i32_16x16x64_i8 v[122:125], v[110:113], v[218:221], v[122:125]
	v_mfma_i32_16x16x64_i8 v[134:137], v[70:73], v[218:221], v[134:137]
	v_mfma_i32_16x16x64_i8 v[134:137], v[66:69], v[214:217], v[134:137]
	v_mfma_i32_16x16x64_i8 v[74:77], v[126:129], v[214:217], v[74:77]
	v_mfma_i32_16x16x64_i8 v[74:77], v[178:181], v[218:221], v[74:77]
	v_mfma_i32_16x16x64_i8 v[94:97], v[178:181], v[186:189], v[94:97]
	v_mfma_i32_16x16x64_i8 v[94:97], v[126:129], v[182:185], v[94:97]
	v_mfma_i32_16x16x64_i8 v[102:105], v[114:117], v[182:185], v[102:105]
	v_mfma_i32_16x16x64_i8 v[102:105], v[118:121], v[186:189], v[102:105]
	v_mfma_i32_16x16x64_i8 v[98:101], v[118:121], v[194:197], v[98:101]
	v_mfma_i32_16x16x64_i8 v[98:101], v[114:117], v[190:193], v[98:101]
	v_mfma_i32_16x16x64_i8 v[86:89], v[126:129], v[190:193], v[86:89]
	v_mfma_i32_16x16x64_i8 v[86:89], v[178:181], v[194:197], v[86:89]
	v_mfma_i32_16x16x64_i8 v[78:81], v[178:181], v[210:213], v[78:81]
	v_mfma_i32_16x16x64_i8 v[78:81], v[126:129], v[198:201], v[78:81]
	v_mfma_i32_16x16x64_i8 v[90:93], v[114:117], v[198:201], v[90:93]
	v_mfma_i32_16x16x64_i8 v[90:93], v[118:121], v[210:213], v[90:93]
	v_mfma_i32_16x16x64_i8 v[82:85], v[118:121], v[218:221], v[82:85]
	v_mfma_i32_16x16x64_i8 v[82:85], v[114:117], v[214:217], v[82:85]
	s_barrier
	s_add_i32 s8, s66, s81
	v_lshl_add_u64 v[168:169], v[168:169], 0, s[92:93]
	s_mov_b32 m0, s8
	ds_read_b128 v[182:185], v177 offset:49152
	ds_read_b128 v[186:189], v177 offset:50176
	ds_read_b128 v[190:193], v177 offset:51200
	ds_read_b128 v[194:197], v177 offset:52224
	ds_read_b128 v[198:201], v177 offset:53248
	ds_read_b128 v[210:213], v177 offset:54272
	ds_read_b128 v[214:217], v177 offset:55296
	ds_read_b128 v[218:221], v177 offset:56320
	global_load_lds_dwordx4 v[168:169], off
	s_add_i32 m0, s8, 0x2000
	s_add_u32 s8, s96, 0x40080
	v_lshl_add_u64 v[168:169], v[206:207], 0, s[92:93]
	s_addc_u32 s9, s97, 0
	s_add_i32 s66, s70, s81
	global_load_lds_dwordx4 v[168:169], off
	v_lshl_add_u64 v[168:169], s[8:9], 0, v[0:1]
	s_mov_b32 m0, s66
	s_nop 0
	global_load_lds_dwordx4 v[168:169], off
	v_lshl_add_u64 v[168:169], s[8:9], 0, v[158:159]
	s_add_i32 m0, s66, 0x2000
	s_nop 0
	global_load_lds_dwordx4 v[168:169], off
	v_lshl_add_u64 v[168:169], v[222:223], 0, s[92:93]
	s_mov_b32 m0, s13
	s_nop 0
	global_load_lds_dwordx4 v[168:169], off
	v_lshl_add_u64 v[168:169], v[224:225], 0, s[92:93]
	s_mov_b32 m0, s12
	s_nop 0
	global_load_lds_dwordx4 v[168:169], off
	s_waitcnt vmcnt(8)
	s_waitcnt lgkmcnt(0)
	s_barrier
	s_waitcnt lgkmcnt(0)
	v_mfma_i32_16x16x64_i8 v[62:65], v[66:69], v[182:185], v[62:65]
	v_mfma_i32_16x16x64_i8 v[62:65], v[70:73], v[186:189], v[62:65]
	v_mfma_i32_16x16x64_i8 v[54:57], v[110:113], v[186:189], v[54:57]
	v_mfma_i32_16x16x64_i8 v[54:57], v[106:109], v[182:185], v[54:57]
	v_mfma_i32_16x16x64_i8 v[46:49], v[106:109], v[190:193], v[46:49]
	v_mfma_i32_16x16x64_i8 v[46:49], v[110:113], v[194:197], v[46:49]
	v_mfma_i32_16x16x64_i8 v[58:61], v[70:73], v[194:197], v[58:61]
	v_mfma_i32_16x16x64_i8 v[58:61], v[66:69], v[190:193], v[58:61]
	v_mfma_i32_16x16x64_i8 v[50:53], v[66:69], v[198:201], v[50:53]
	v_mfma_i32_16x16x64_i8 v[50:53], v[70:73], v[210:213], v[50:53]
	v_mfma_i32_16x16x64_i8 v[38:41], v[110:113], v[210:213], v[38:41]
	v_mfma_i32_16x16x64_i8 v[38:41], v[106:109], v[198:201], v[38:41]
	v_mfma_i32_16x16x64_i8 v[34:37], v[106:109], v[214:217], v[34:37]
	v_mfma_i32_16x16x64_i8 v[34:37], v[110:113], v[218:221], v[34:37]
	v_mfma_i32_16x16x64_i8 v[42:45], v[70:73], v[218:221], v[42:45]
	v_mfma_i32_16x16x64_i8 v[42:45], v[66:69], v[214:217], v[42:45]
	v_mfma_i32_16x16x64_i8 v[2:5], v[126:129], v[214:217], v[2:5]
	v_mfma_i32_16x16x64_i8 v[2:5], v[178:181], v[218:221], v[2:5]
	v_mfma_i32_16x16x64_i8 v[22:25], v[178:181], v[186:189], v[22:25]
	v_mfma_i32_16x16x64_i8 v[22:25], v[126:129], v[182:185], v[22:25]
	v_mfma_i32_16x16x64_i8 v[30:33], v[114:117], v[182:185], v[30:33]
	v_mfma_i32_16x16x64_i8 v[30:33], v[118:121], v[186:189], v[30:33]
	v_mfma_i32_16x16x64_i8 v[26:29], v[118:121], v[194:197], v[26:29]
	v_mfma_i32_16x16x64_i8 v[26:29], v[114:117], v[190:193], v[26:29]
	v_mfma_i32_16x16x64_i8 v[14:17], v[126:129], v[190:193], v[14:17]
	v_mfma_i32_16x16x64_i8 v[14:17], v[178:181], v[194:197], v[14:17]
	v_mfma_i32_16x16x64_i8 v[6:9], v[178:181], v[210:213], v[6:9]
	v_mfma_i32_16x16x64_i8 v[6:9], v[126:129], v[198:201], v[6:9]
	v_mfma_i32_16x16x64_i8 v[18:21], v[114:117], v[198:201], v[18:21]
	v_mfma_i32_16x16x64_i8 v[18:21], v[118:121], v[210:213], v[18:21]
	v_mfma_i32_16x16x64_i8 v[10:13], v[118:121], v[218:221], v[10:13]
	v_mfma_i32_16x16x64_i8 v[10:13], v[114:117], v[214:217], v[10:13]
	s_barrier
	s_add_i32 s10, s10, 2
	s_add_u32 s69, s69, 0x100
	s_addc_u32 s68, s68, 0
	s_cmp_gt_u32 s10, 13
	s_mov_b64 s[8:9], s[84:85]
	s_cbranch_scc0 .LBB0_291
	s_branch .Lpeelx291
; #define PG8_STAGE(bufoff, gbase, voff) do { _Pragma("unroll") for (int _i = 0; _i < 2; ++_i) \
;         __builtin_amdgcn_global_load_lds((const unsigned*)((const char*)(gbase) + (voff)[_i]), (PG8_LAS unsigned*)(lds + (bufoff) + ldsw + _i * 8192), 16, 0, 0); } while (0)
; #define PG8_LDA(dst, b, h) do { _Pragma("unroll") for (int m = 0; m < 4; ++m) _Pragma("unroll") for (int k = 0; k < 2; ++k) dst[m][k] = *(const PG8_LAS bf16x8*)(lds + PG8_SA(b, h) + aoff + m * 2048 + k * 1024); } while (0)
; #define PG8_LDB(dst, b, h) do { _Pragma("unroll") for (int n = 0; n < 2; ++n) _Pragma("unroll") for (int k = 0; k < 2; ++k) dst[n][k] = *(const PG8_LAS bf16x8*)(lds + PG8_SB(b, h) + boff + n * 2048 + k * 1024); } while (0)
; #define PG8_MMA(ai, bj, At, Bt) do { __builtin_amdgcn_s_setprio(1); _Pragma("unroll") for (int m = 0; m < 4; ++m) _Pragma("unroll") for (int n = 0; n < 2; ++n) _Pragma("unroll") for (int k = 0; k < 2; ++k) \
;         acc[ai][bj][m][n] = mma16<Epi::I8>(Bt[n][k], At[m][k], acc[ai][bj][m][n]); __builtin_amdgcn_s_setprio(0); } while (0)
; #define PG8_WAIT_V(n) asm volatile("s_waitcnt vmcnt(" #n ")" ::: "memory")
; #define PG8_WAIT_L(n) asm volatile("s_waitcnt lgkmcnt(" #n ")" ::: "memory")
; template <class Epi, class Sched, bool ALIGN_EPI = false, bool SP2 = false>
; __device__ __forceinline__ void gemm_phase(PG8_LAS unsigned char* lds, const Gemm g, const Sched& S, const Epi& E) {
;     ...
;         for (int t = 0; t < nt; t += 2) {
;             const bool last = (t == nt - 2);
;             const char* a1 = cA + (size_t)(t + 1) * kstep;
;             const char* a2 = last ? nA : cA + (size_t)(t + 2) * kstep; const char* b2 = last ? nB : cB + (size_t)(t + 2) * kstep;
;             const char* a3 = a2 + kstep; const char* b3 = b2 + kstep;
;             if (last && has_next) S.a_ready(nxt);
;             if constexpr (SP2) {
;             PG8_LDB(B0, 0, 0); PG8_LDB(B1, 0, 1); PG8_SCHED; PG8_LDA(At, 0, 0); PG8_STAGE(PG8_SA(1, 1), a1 + hstep, voffA);
;             PG8_WAIT_V(8); PG8_WAIT_L(0); PG8_BAR; PG8_MMA(0, 0, At, B0); PG8_MMA(0, 1, At, B1); PG8_BAR; PG8_SCHED;
;             PG8_LDA(At, 0, 1); PG8_STAGE(PG8_SB(0, 0), b2, voffB); PG8_STAGE(PG8_SB(0, 1), b2 + hstep, voffB); PG8_STAGE(PG8_SA(0, 0), a2, voffA);
;             PG8_WAIT_V(8); PG8_WAIT_L(0); PG8_BAR; PG8_MMA(1, 0, At, B0); PG8_MMA(1, 1, At, B1); PG8_BAR; PG8_SCHED;
.LBB0_291:
	s_add_u32 s84, s8, 0x100
	s_addc_u32 s85, s9, 0
	s_add_i32 s66, 0, 0x10000
	s_cmp_eq_u32 s10, 12
	s_cselect_b32 vcc_hi, s5, s85
	s_cselect_b32 vcc_lo, s7, s84
	s_cselect_b32 s97, s11, s68
	s_cselect_b32 s96, s67, s69
	s_add_i32 s70, 0, 0x14000
	v_add_u32_e32 v110, s66, v175
	v_add_u32_e32 v168, s70, v175
	s_waitcnt vmcnt(0)
	ds_read_b128 v[66:69], v110
	ds_read_b128 v[70:73], v110 offset:1024
	ds_read_b128 v[106:109], v110 offset:2048
	ds_read_b128 v[110:113], v110 offset:3072
	ds_read_b128 v[114:117], v168
	ds_read_b128 v[118:121], v168 offset:1024
	ds_read_b128 v[126:129], v168 offset:2048
	ds_read_b128 v[178:181], v168 offset:3072
	v_lshl_add_u64 v[168:169], s[8:9], 0, v[164:165]
	s_add_i32 m0, s1, 0xc000
	ds_read_b128 v[182:185], v177
	ds_read_b128 v[186:189], v177 offset:1024
	ds_read_b128 v[190:193], v177 offset:2048
	ds_read_b128 v[194:197], v177 offset:3072
	ds_read_b128 v[198:201], v177 offset:4096
	ds_read_b128 v[210:213], v177 offset:5120
	ds_read_b128 v[214:217], v177 offset:6144
	ds_read_b128 v[218:221], v177 offset:7168
	global_load_lds_dwordx4 v[168:169], off
	v_lshl_add_u64 v[168:169], s[8:9], 0, v[166:167]
	s_add_i32 m0, s1, 0xe000
	s_nop 0
	global_load_lds_dwordx4 v[168:169], off
	s_waitcnt vmcnt(8)
	s_waitcnt lgkmcnt(0)
	s_barrier
	s_waitcnt lgkmcnt(0)
	v_mfma_i32_16x16x64_i8 v[154:157], v[66:69], v[182:185], v[154:157]
	v_mfma_i32_16x16x64_i8 v[154:157], v[70:73], v[186:189], v[154:157]
	v_mfma_i32_16x16x64_i8 v[146:149], v[110:113], v[186:189], v[146:149]
	v_mfma_i32_16x16x64_i8 v[146:149], v[106:109], v[182:185], v[146:149]
	v_mfma_i32_16x16x64_i8 v[138:141], v[106:109], v[190:193], v[138:141]
	v_mfma_i32_16x16x64_i8 v[138:141], v[110:113], v[194:197], v[138:141]
	v_mfma_i32_16x16x64_i8 v[150:153], v[70:73], v[194:197], v[150:153]
	v_mfma_i32_16x16x64_i8 v[150:153], v[66:69], v[190:193], v[150:153]
	v_mfma_i32_16x16x64_i8 v[142:145], v[66:69], v[198:201], v[142:145]
	v_mfma_i32_16x16x64_i8 v[142:145], v[70:73], v[210:213], v[142:145]
	v_mfma_i32_16x16x64_i8 v[130:133], v[110:113], v[210:213], v[130:133]
	v_mfma_i32_16x16x64_i8 v[130:133], v[106:109], v[198:201], v[130:133]
	v_mfma_i32_16x16x64_i8 v[122:125], v[106:109], v[214:217], v[122:125]
	v_mfma_i32_16x16x64_i8 v[122:125], v[110:113], v[218:221], v[122:125]
	v_mfma_i32_16x16x64_i8 v[134:137], v[70:73], v[218:221], v[134:137]
	v_mfma_i32_16x16x64_i8 v[134:137], v[66:69], v[214:217], v[134:137]
	v_mfma_i32_16x16x64_i8 v[74:77], v[126:129], v[214:217], v[74:77]
	v_mfma_i32_16x16x64_i8 v[74:77], v[178:181], v[218:221], v[74:77]
	v_mfma_i32_16x16x64_i8 v[94:97], v[178:181], v[186:189], v[94:97]
	v_mfma_i32_16x16x64_i8 v[94:97], v[126:129], v[182:185], v[94:97]
	v_mfma_i32_16x16x64_i8 v[102:105], v[114:117], v[182:185], v[102:105]
	v_mfma_i32_16x16x64_i8 v[102:105], v[118:121], v[186:189], v[102:105]
	v_mfma_i32_16x16x64_i8 v[98:101], v[118:121], v[194:197], v[98:101]
	v_mfma_i32_16x16x64_i8 v[98:101], v[114:117], v[190:193], v[98:101]
	v_mfma_i32_16x16x64_i8 v[86:89], v[126:129], v[190:193], v[86:89]
	v_mfma_i32_16x16x64_i8 v[86:89], v[178:181], v[194:197], v[86:89]
	v_mfma_i32_16x16x64_i8 v[78:81], v[178:181], v[210:213], v[78:81]
	v_mfma_i32_16x16x64_i8 v[78:81], v[126:129], v[198:201], v[78:81]
	v_mfma_i32_16x16x64_i8 v[90:93], v[114:117], v[198:201], v[90:93]
	v_mfma_i32_16x16x64_i8 v[90:93], v[118:121], v[210:213], v[90:93]
	v_mfma_i32_16x16x64_i8 v[82:85], v[118:121], v[218:221], v[82:85]
	v_mfma_i32_16x16x64_i8 v[82:85], v[114:117], v[214:217], v[82:85]
	s_barrier
	s_add_i32 s8, s66, s81
	v_lshl_add_u64 v[168:169], s[96:97], 0, v[0:1]
	s_mov_b32 m0, s8
	ds_read_b128 v[182:185], v177 offset:16384
	ds_read_b128 v[186:189], v177 offset:17408
	ds_read_b128 v[190:193], v177 offset:18432
	ds_read_b128 v[194:197], v177 offset:19456
	ds_read_b128 v[198:201], v177 offset:20480
	ds_read_b128 v[210:213], v177 offset:21504
	ds_read_b128 v[214:217], v177 offset:22528
	ds_read_b128 v[218:221], v177 offset:23552
	global_load_lds_dwordx4 v[168:169], off
	s_add_i32 m0, s8, 0x2000
	s_add_u32 s8, s96, 0x40000
	v_lshl_add_u64 v[206:207], s[96:97], 0, v[158:159]
	s_addc_u32 s9, s97, 0
	s_add_i32 s66, s70, s81
	global_load_lds_dwordx4 v[206:207], off
	v_lshl_add_u64 v[222:223], s[8:9], 0, v[0:1]
	s_mov_b32 m0, s66
	v_lshl_add_u64 v[224:225], vcc, 0, v[160:161]
	global_load_lds_dwordx4 v[222:223], off
	v_lshl_add_u64 v[222:223], s[8:9], 0, v[158:159]
	s_add_i32 m0, s66, 0x2000
	s_nop 0
	global_load_lds_dwordx4 v[222:223], off
	v_lshl_add_u64 v[222:223], vcc, 0, v[162:163]
	s_mov_b32 m0, s1
	s_nop 0
	global_load_lds_dwordx4 v[222:223], off
	s_mov_b32 m0, s58
	s_nop 0
	global_load_lds_dwordx4 v[224:225], off
	s_waitcnt vmcnt(8)
	s_waitcnt lgkmcnt(0)
	s_barrier
; #define PG8_STAGE(bufoff, gbase, voff) do { _Pragma("unroll") for (int _i = 0; _i < 2; ++_i) \
;         __builtin_amdgcn_global_load_lds((const unsigned*)((const char*)(gbase) + (voff)[_i]), (PG8_LAS unsigned*)(lds + (bufoff) + ldsw + _i * 8192), 16, 0, 0); } while (0)
; #define PG8_LDA(dst, b, h) do { _Pragma("unroll") for (int m = 0; m < 4; ++m) _Pragma("unroll") for (int k = 0; k < 2; ++k) dst[m][k] = *(const PG8_LAS bf16x8*)(lds + PG8_SA(b, h) + aoff + m * 2048 + k * 1024); } while (0)
; #define PG8_LDB(dst, b, h) do { _Pragma("unroll") for (int n = 0; n < 2; ++n) _Pragma("unroll") for (int k = 0; k < 2; ++k) dst[n][k] = *(const PG8_LAS bf16x8*)(lds + PG8_SB(b, h) + boff + n * 2048 + k * 1024); } while (0)
; #define PG8_MMA(ai, bj, At, Bt) do { __builtin_amdgcn_s_setprio(1); _Pragma("unroll") for (int m = 0; m < 4; ++m) _Pragma("unroll") for (int n = 0; n < 2; ++n) _Pragma("unroll") for (int k = 0; k < 2; ++k) \
;         acc[ai][bj][m][n] = mma16<Epi::I8>(Bt[n][k], At[m][k], acc[ai][bj][m][n]); __builtin_amdgcn_s_setprio(0); } while (0)
; #define PG8_WAIT_V(n) asm volatile("s_waitcnt vmcnt(" #n ")" ::: "memory")
; #define PG8_WAIT_L(n) asm volatile("s_waitcnt lgkmcnt(" #n ")" ::: "memory")
; #define PG8_BAR __builtin_amdgcn_s_barrier()
; #define PG8_SCHED __builtin_amdgcn_sched_barrier(0)
; template <class Epi, class Sched, bool ALIGN_EPI = false, bool SP2 = false>
; __device__ __forceinline__ void gemm_phase(PG8_LAS unsigned char* lds, const Gemm g, const Sched& S, const Epi& E) {
;     ...
;             PG8_LDA(At, 0, 1); PG8_STAGE(PG8_SB(0, 0), b2, voffB); PG8_STAGE(PG8_SB(0, 1), b2 + hstep, voffB); PG8_STAGE(PG8_SA(0, 0), a2, voffA);
;             PG8_WAIT_V(8); PG8_WAIT_L(0); PG8_BAR; PG8_MMA(1, 0, At, B0); PG8_MMA(1, 1, At, B1); PG8_BAR; PG8_SCHED;
;             PG8_LDB(B0, 1, 0); PG8_LDB(B1, 1, 1); PG8_SCHED; PG8_LDA(At, 1, 0); PG8_STAGE(PG8_SA(0, 1), a2 + hstep, voffA);
;             PG8_WAIT_V(8); PG8_WAIT_L(0); PG8_BAR; PG8_MMA(0, 0, At, B0); PG8_MMA(0, 1, At, B1); PG8_BAR; PG8_SCHED;
	s_waitcnt lgkmcnt(0)
	v_mfma_i32_16x16x64_i8 v[62:65], v[66:69], v[182:185], v[62:65]
	v_mfma_i32_16x16x64_i8 v[62:65], v[70:73], v[186:189], v[62:65]
	v_mfma_i32_16x16x64_i8 v[54:57], v[110:113], v[186:189], v[54:57]
	v_mfma_i32_16x16x64_i8 v[54:57], v[106:109], v[182:185], v[54:57]
	v_mfma_i32_16x16x64_i8 v[46:49], v[106:109], v[190:193], v[46:49]
	v_mfma_i32_16x16x64_i8 v[46:49], v[110:113], v[194:197], v[46:49]
	v_mfma_i32_16x16x64_i8 v[58:61], v[70:73], v[194:197], v[58:61]
	v_mfma_i32_16x16x64_i8 v[58:61], v[66:69], v[190:193], v[58:61]
	v_mfma_i32_16x16x64_i8 v[50:53], v[66:69], v[198:201], v[50:53]
	v_mfma_i32_16x16x64_i8 v[50:53], v[70:73], v[210:213], v[50:53]
	v_mfma_i32_16x16x64_i8 v[38:41], v[110:113], v[210:213], v[38:41]
	v_mfma_i32_16x16x64_i8 v[38:41], v[106:109], v[198:201], v[38:41]
	v_mfma_i32_16x16x64_i8 v[34:37], v[106:109], v[214:217], v[34:37]
	v_mfma_i32_16x16x64_i8 v[34:37], v[110:113], v[218:221], v[34:37]
	v_mfma_i32_16x16x64_i8 v[42:45], v[70:73], v[218:221], v[42:45]
	v_mfma_i32_16x16x64_i8 v[42:45], v[66:69], v[214:217], v[42:45]
	v_mfma_i32_16x16x64_i8 v[2:5], v[126:129], v[214:217], v[2:5]
	v_mfma_i32_16x16x64_i8 v[2:5], v[178:181], v[218:221], v[2:5]
	v_mfma_i32_16x16x64_i8 v[22:25], v[178:181], v[186:189], v[22:25]
	v_mfma_i32_16x16x64_i8 v[22:25], v[126:129], v[182:185], v[22:25]
	v_mfma_i32_16x16x64_i8 v[30:33], v[114:117], v[182:185], v[30:33]
	v_mfma_i32_16x16x64_i8 v[30:33], v[118:121], v[186:189], v[30:33]
	v_mfma_i32_16x16x64_i8 v[26:29], v[118:121], v[194:197], v[26:29]
	v_mfma_i32_16x16x64_i8 v[26:29], v[114:117], v[190:193], v[26:29]
	v_mfma_i32_16x16x64_i8 v[14:17], v[126:129], v[190:193], v[14:17]
	v_mfma_i32_16x16x64_i8 v[14:17], v[178:181], v[194:197], v[14:17]
	v_mfma_i32_16x16x64_i8 v[6:9], v[178:181], v[210:213], v[6:9]
	v_mfma_i32_16x16x64_i8 v[6:9], v[126:129], v[198:201], v[6:9]
	v_mfma_i32_16x16x64_i8 v[18:21], v[114:117], v[198:201], v[18:21]
	v_mfma_i32_16x16x64_i8 v[18:21], v[118:121], v[210:213], v[18:21]
	v_mfma_i32_16x16x64_i8 v[10:13], v[118:121], v[218:221], v[10:13]
	v_mfma_i32_16x16x64_i8 v[10:13], v[114:117], v[214:217], v[10:13]
	s_barrier
	s_add_i32 s66, 0, 0x18000
	s_add_i32 s70, 0, 0x1c000
	v_add_u32_e32 v110, s66, v175
	v_add_u32_e32 v170, s70, v175
	ds_read_b128 v[66:69], v110
	ds_read_b128 v[70:73], v110 offset:1024
	ds_read_b128 v[106:109], v110 offset:2048
	ds_read_b128 v[110:113], v110 offset:3072
	ds_read_b128 v[114:117], v170
	ds_read_b128 v[118:121], v170 offset:1024
	ds_read_b128 v[126:129], v170 offset:2048
	ds_read_b128 v[178:181], v170 offset:3072
	s_add_u32 s8, vcc_lo, 0x40000
	s_addc_u32 s9, vcc_hi, 0
	s_mov_b32 m0, s80
	v_lshl_add_u64 v[226:227], s[8:9], 0, v[162:163]
	ds_read_b128 v[182:185], v177 offset:32768
	ds_read_b128 v[186:189], v177 offset:33792
	ds_read_b128 v[190:193], v177 offset:34816
	ds_read_b128 v[194:197], v177 offset:35840
	ds_read_b128 v[198:201], v177 offset:36864
	ds_read_b128 v[210:213], v177 offset:37888
	ds_read_b128 v[214:217], v177 offset:38912
	ds_read_b128 v[218:221], v177 offset:39936
	global_load_lds_dwordx4 v[226:227], off
	v_lshl_add_u64 v[226:227], s[8:9], 0, v[160:161]
	s_mov_b32 m0, s0
	s_nop 0
	global_load_lds_dwordx4 v[226:227], off
	s_waitcnt vmcnt(8)
	s_waitcnt lgkmcnt(0)
	s_barrier
	s_waitcnt lgkmcnt(0)
	v_mfma_i32_16x16x64_i8 v[154:157], v[66:69], v[182:185], v[154:157]
	v_mfma_i32_16x16x64_i8 v[154:157], v[70:73], v[186:189], v[154:157]
	v_mfma_i32_16x16x64_i8 v[146:149], v[110:113], v[186:189], v[146:149]
	v_mfma_i32_16x16x64_i8 v[146:149], v[106:109], v[182:185], v[146:149]
	v_mfma_i32_16x16x64_i8 v[138:141], v[106:109], v[190:193], v[138:141]
	v_mfma_i32_16x16x64_i8 v[138:141], v[110:113], v[194:197], v[138:141]
	v_mfma_i32_16x16x64_i8 v[150:153], v[70:73], v[194:197], v[150:153]
	v_mfma_i32_16x16x64_i8 v[150:153], v[66:69], v[190:193], v[150:153]
	v_mfma_i32_16x16x64_i8 v[142:145], v[66:69], v[198:201], v[142:145]
	v_mfma_i32_16x16x64_i8 v[142:145], v[70:73], v[210:213], v[142:145]
	v_mfma_i32_16x16x64_i8 v[130:133], v[110:113], v[210:213], v[130:133]
	v_mfma_i32_16x16x64_i8 v[130:133], v[106:109], v[198:201], v[130:133]
	v_mfma_i32_16x16x64_i8 v[122:125], v[106:109], v[214:217], v[122:125]
	v_mfma_i32_16x16x64_i8 v[122:125], v[110:113], v[218:221], v[122:125]
	v_mfma_i32_16x16x64_i8 v[134:137], v[70:73], v[218:221], v[134:137]
	v_mfma_i32_16x16x64_i8 v[134:137], v[66:69], v[214:217], v[134:137]
	v_mfma_i32_16x16x64_i8 v[74:77], v[126:129], v[214:217], v[74:77]
	v_mfma_i32_16x16x64_i8 v[74:77], v[178:181], v[218:221], v[74:77]
	v_mfma_i32_16x16x64_i8 v[94:97], v[178:181], v[186:189], v[94:97]
	v_mfma_i32_16x16x64_i8 v[94:97], v[126:129], v[182:185], v[94:97]
	v_mfma_i32_16x16x64_i8 v[102:105], v[114:117], v[182:185], v[102:105]
	v_mfma_i32_16x16x64_i8 v[102:105], v[118:121], v[186:189], v[102:105]
	v_mfma_i32_16x16x64_i8 v[98:101], v[118:121], v[194:197], v[98:101]
	v_mfma_i32_16x16x64_i8 v[98:101], v[114:117], v[190:193], v[98:101]
	v_mfma_i32_16x16x64_i8 v[86:89], v[126:129], v[190:193], v[86:89]
	v_mfma_i32_16x16x64_i8 v[86:89], v[178:181], v[194:197], v[86:89]
	v_mfma_i32_16x16x64_i8 v[78:81], v[178:181], v[210:213], v[78:81]
	v_mfma_i32_16x16x64_i8 v[78:81], v[126:129], v[198:201], v[78:81]
	v_mfma_i32_16x16x64_i8 v[90:93], v[114:117], v[198:201], v[90:93]
	v_mfma_i32_16x16x64_i8 v[90:93], v[118:121], v[210:213], v[90:93]
	v_mfma_i32_16x16x64_i8 v[82:85], v[118:121], v[218:221], v[82:85]
	v_mfma_i32_16x16x64_i8 v[82:85], v[114:117], v[214:217], v[82:85]
	s_barrier
; #define PG8_STAGE(bufoff, gbase, voff) do { _Pragma("unroll") for (int _i = 0; _i < 2; ++_i) \
;         __builtin_amdgcn_global_load_lds((const unsigned*)((const char*)(gbase) + (voff)[_i]), (PG8_LAS unsigned*)(lds + (bufoff) + ldsw + _i * 8192), 16, 0, 0); } while (0)
; #define PG8_LDA(dst, b, h) do { _Pragma("unroll") for (int m = 0; m < 4; ++m) _Pragma("unroll") for (int k = 0; k < 2; ++k) dst[m][k] = *(const PG8_LAS bf16x8*)(lds + PG8_SA(b, h) + aoff + m * 2048 + k * 1024); } while (0)
; #define PG8_MMA(ai, bj, At, Bt) do { __builtin_amdgcn_s_setprio(1); _Pragma("unroll") for (int m = 0; m < 4; ++m) _Pragma("unroll") for (int n = 0; n < 2; ++n) _Pragma("unroll") for (int k = 0; k < 2; ++k) \
;         acc[ai][bj][m][n] = mma16<Epi::I8>(Bt[n][k], At[m][k], acc[ai][bj][m][n]); __builtin_amdgcn_s_setprio(0); } while (0)
; #define PG8_WAIT_V(n) asm volatile("s_waitcnt vmcnt(" #n ")" ::: "memory")
; #define PG8_WAIT_L(n) asm volatile("s_waitcnt lgkmcnt(" #n ")" ::: "memory")
; #define PG8_BAR __builtin_amdgcn_s_barrier()
; #define PG8_SCHED __builtin_amdgcn_sched_barrier(0)
; template <class Epi, class Sched, bool ALIGN_EPI = false, bool SP2 = false>
; __device__ __forceinline__ void gemm_phase(PG8_LAS unsigned char* lds, const Gemm g, const Sched& S, const Epi& E) {
;     ...
;             PG8_LDA(At, 1, 1); PG8_STAGE(PG8_SB(1, 0), b3, voffB); PG8_STAGE(PG8_SB(1, 1), b3 + hstep, voffB); PG8_STAGE(PG8_SA(1, 0), a3, voffA);
;             PG8_WAIT_V(8); PG8_WAIT_L(0); PG8_BAR; PG8_MMA(1, 0, At, B0); PG8_MMA(1, 1, At, B1); PG8_BAR; PG8_SCHED;
	s_add_i32 s8, s66, s81
	v_lshl_add_u64 v[168:169], v[168:169], 0, s[92:93]
	s_mov_b32 m0, s8
	ds_read_b128 v[182:185], v177 offset:49152
	ds_read_b128 v[186:189], v177 offset:50176
	ds_read_b128 v[190:193], v177 offset:51200
	ds_read_b128 v[194:197], v177 offset:52224
	ds_read_b128 v[198:201], v177 offset:53248
	ds_read_b128 v[210:213], v177 offset:54272
	ds_read_b128 v[214:217], v177 offset:55296
	ds_read_b128 v[218:221], v177 offset:56320
	global_load_lds_dwordx4 v[168:169], off
	s_add_i32 m0, s8, 0x2000
	s_add_u32 s8, s96, 0x40080
	v_lshl_add_u64 v[168:169], v[206:207], 0, s[92:93]
	s_addc_u32 s9, s97, 0
	s_add_i32 s66, s70, s81
	global_load_lds_dwordx4 v[168:169], off
	v_lshl_add_u64 v[168:169], s[8:9], 0, v[0:1]
	s_mov_b32 m0, s66
	s_nop 0
	global_load_lds_dwordx4 v[168:169], off
	v_lshl_add_u64 v[168:169], s[8:9], 0, v[158:159]
	s_add_i32 m0, s66, 0x2000
	s_nop 0
	global_load_lds_dwordx4 v[168:169], off
	v_lshl_add_u64 v[168:169], v[222:223], 0, s[92:93]
	s_mov_b32 m0, s13
	s_nop 0
	global_load_lds_dwordx4 v[168:169], off
	v_lshl_add_u64 v[168:169], v[224:225], 0, s[92:93]
	s_mov_b32 m0, s12
	s_nop 0
	global_load_lds_dwordx4 v[168:169], off
	s_waitcnt vmcnt(8)
	s_waitcnt lgkmcnt(0)
	s_barrier
	s_waitcnt lgkmcnt(0)
	v_mfma_i32_16x16x64_i8 v[62:65], v[66:69], v[182:185], v[62:65]
	v_mfma_i32_16x16x64_i8 v[62:65], v[70:73], v[186:189], v[62:65]
	v_mfma_i32_16x16x64_i8 v[54:57], v[110:113], v[186:189], v[54:57]
	v_mfma_i32_16x16x64_i8 v[54:57], v[106:109], v[182:185], v[54:57]
	v_mfma_i32_16x16x64_i8 v[46:49], v[106:109], v[190:193], v[46:49]
	v_mfma_i32_16x16x64_i8 v[46:49], v[110:113], v[194:197], v[46:49]
	v_mfma_i32_16x16x64_i8 v[58:61], v[70:73], v[194:197], v[58:61]
	v_mfma_i32_16x16x64_i8 v[58:61], v[66:69], v[190:193], v[58:61]
	v_mfma_i32_16x16x64_i8 v[50:53], v[66:69], v[198:201], v[50:53]
	v_mfma_i32_16x16x64_i8 v[50:53], v[70:73], v[210:213], v[50:53]
	v_mfma_i32_16x16x64_i8 v[38:41], v[110:113], v[210:213], v[38:41]
	v_mfma_i32_16x16x64_i8 v[38:41], v[106:109], v[198:201], v[38:41]
	v_mfma_i32_16x16x64_i8 v[34:37], v[106:109], v[214:217], v[34:37]
	v_mfma_i32_16x16x64_i8 v[34:37], v[110:113], v[218:221], v[34:37]
	v_mfma_i32_16x16x64_i8 v[42:45], v[70:73], v[218:221], v[42:45]
	v_mfma_i32_16x16x64_i8 v[42:45], v[66:69], v[214:217], v[42:45]
	v_mfma_i32_16x16x64_i8 v[2:5], v[126:129], v[214:217], v[2:5]
	v_mfma_i32_16x16x64_i8 v[2:5], v[178:181], v[218:221], v[2:5]
	v_mfma_i32_16x16x64_i8 v[22:25], v[178:181], v[186:189], v[22:25]
	v_mfma_i32_16x16x64_i8 v[22:25], v[126:129], v[182:185], v[22:25]
	v_mfma_i32_16x16x64_i8 v[30:33], v[114:117], v[182:185], v[30:33]
	v_mfma_i32_16x16x64_i8 v[30:33], v[118:121], v[186:189], v[30:33]
	v_mfma_i32_16x16x64_i8 v[26:29], v[118:121], v[194:197], v[26:29]
	v_mfma_i32_16x16x64_i8 v[26:29], v[114:117], v[190:193], v[26:29]
	v_mfma_i32_16x16x64_i8 v[14:17], v[126:129], v[190:193], v[14:17]
	v_mfma_i32_16x16x64_i8 v[14:17], v[178:181], v[194:197], v[14:17]
	v_mfma_i32_16x16x64_i8 v[6:9], v[178:181], v[210:213], v[6:9]
	v_mfma_i32_16x16x64_i8 v[6:9], v[126:129], v[198:201], v[6:9]
	v_mfma_i32_16x16x64_i8 v[18:21], v[114:117], v[198:201], v[18:21]
	v_mfma_i32_16x16x64_i8 v[18:21], v[118:121], v[210:213], v[18:21]
	v_mfma_i32_16x16x64_i8 v[10:13], v[118:121], v[218:221], v[10:13]
	v_mfma_i32_16x16x64_i8 v[10:13], v[114:117], v[214:217], v[10:13]
	s_barrier
	s_add_i32 s10, s10, 2
	s_add_u32 s69, s69, 0x100
	s_addc_u32 s68, s68, 0
	s_cmp_gt_u32 s10, 13
	s_mov_b64 s[8:9], s[84:85]
	s_cbranch_scc0 .LBB0_291

; #define PG8_STAGE(bufoff, gbase, voff) do { _Pragma("unroll") for (int _i = 0; _i < 2; ++_i) \
;         __builtin_amdgcn_global_load_lds((const unsigned*)((const char*)(gbase) + (voff)[_i]), (PG8_LAS unsigned*)(lds + (bufoff) + ldsw + _i * 8192), 16, 0, 0); } while (0)
; #define PG8_LDA(dst, b, h) do { _Pragma("unroll") for (int m = 0; m < 4; ++m) _Pragma("unroll") for (int k = 0; k < 2; ++k) dst[m][k] = *(const PG8_LAS bf16x8*)(lds + PG8_SA(b, h) + aoff + m * 2048 + k * 1024); } while (0)
; #define PG8_LDB(dst, b, h) do { _Pragma("unroll") for (int n = 0; n < 2; ++n) _Pragma("unroll") for (int k = 0; k < 2; ++k) dst[n][k] = *(const PG8_LAS bf16x8*)(lds + PG8_SB(b, h) + boff + n * 2048 + k * 1024); } while (0)
; #define PG8_MMA(ai, bj, At, Bt) do { __builtin_amdgcn_s_setprio(1); _Pragma("unroll") for (int m = 0; m < 4; ++m) _Pragma("unroll") for (int n = 0; n < 2; ++n) _Pragma("unroll") for (int k = 0; k < 2; ++k) \
;         acc[ai][bj][m][n] = mma16<Epi::I8>(Bt[n][k], At[m][k], acc[ai][bj][m][n]); __builtin_amdgcn_s_setprio(0); } while (0)
; #define PG8_WAIT_V(n) asm volatile("s_waitcnt vmcnt(" #n ")" ::: "memory")
; #define PG8_WAIT_L(n) asm volatile("s_waitcnt lgkmcnt(" #n ")" ::: "memory")
; template <class Epi, class Sched, bool ALIGN_EPI = false, bool SP2 = false>
; __device__ __forceinline__ void gemm_phase(PG8_LAS unsigned char* lds, const Gemm g, const Sched& S, const Epi& E) {
;     ...
;         for (int t = 0; t < nt; t += 2) {
;             const bool last = (t == nt - 2);
;             const char* a1 = cA + (size_t)(t + 1) * kstep;
;             const char* a2 = last ? nA : cA + (size_t)(t + 2) * kstep; const char* b2 = last ? nB : cB + (size_t)(t + 2) * kstep;
;             const char* a3 = a2 + kstep; const char* b3 = b2 + kstep;
;             if (last && has_next) S.a_ready(nxt);
;             if constexpr (SP2) {
;             PG8_LDB(B0, 0, 0); PG8_LDB(B1, 0, 1); PG8_SCHED; PG8_LDA(At, 0, 0); PG8_STAGE(PG8_SA(1, 1), a1 + hstep, voffA);
;             PG8_WAIT_V(8); PG8_WAIT_L(0); PG8_BAR; PG8_MMA(0, 0, At, B0); PG8_MMA(0, 1, At, B1); PG8_BAR; PG8_SCHED;
;             PG8_LDA(At, 0, 1); PG8_STAGE(PG8_SB(0, 0), b2, voffB); PG8_STAGE(PG8_SB(0, 1), b2 + hstep, voffB); PG8_STAGE(PG8_SA(0, 0), a2, voffA);
;             PG8_WAIT_V(8); PG8_WAIT_L(0); PG8_BAR; PG8_MMA(1, 0, At, B0); PG8_MMA(1, 1, At, B1); PG8_BAR; PG8_SCHED;
.Lpeel385:
	s_add_u32 s70, s8, 0x100
	s_addc_u32 s71, s9, 0
	s_add_i32 s84, 0, 0x10000
	s_cmp_eq_u32 s5, 12
	s_cselect_b32 vcc_hi, s1, s71
	s_cselect_b32 vcc_lo, s7, s70
	v_add_u32_e32 v0, s84, v214
	s_cselect_b32 s83, s69, s68
	s_cselect_b32 s82, s81, s85
	s_add_i32 s10, 0, 0x14000
	ds_read_b128 v[44:47], v0
	ds_read_b128 v[52:55], v0 offset:1024
	ds_read_b128 v[60:63], v0 offset:2048
	ds_read_b128 v[64:67], v0 offset:3072
	v_add_u32_e32 v0, s10, v214
	ds_read_b128 v[84:87], v0
	ds_read_b128 v[88:91], v0 offset:1024
	ds_read_b128 v[92:95], v0 offset:2048
	ds_read_b128 v[100:103], v0 offset:3072
	v_lshl_add_u64 v[2:3], s[8:9], 0, v[184:185]
	s_add_i32 m0, s13, 0xc000
	ds_read_b128 v[124:127], v215
	ds_read_b128 v[128:131], v215 offset:1024
	ds_read_b128 v[140:143], v215 offset:2048
	ds_read_b128 v[188:191], v215 offset:3072
	ds_read_b128 v[192:195], v215 offset:4096
	ds_read_b128 v[196:199], v215 offset:5120
	ds_read_b128 v[216:219], v215 offset:6144
	ds_read_b128 v[220:223], v215 offset:7168
	global_load_lds_dwordx4 v[2:3], off
	v_lshl_add_u64 v[2:3], s[8:9], 0, v[186:187]
	s_add_i32 m0, s13, 0xe000
	s_nop 0
	global_load_lds_dwordx4 v[2:3], off
	s_waitcnt vmcnt(8)
	s_waitcnt lgkmcnt(0)
	s_barrier
	s_waitcnt lgkmcnt(0)
	v_mfma_i32_16x16x64_i8 v[172:175], v[44:47], v[124:127], 0
	v_mfma_i32_16x16x64_i8 v[172:175], v[52:55], v[128:131], v[172:175]
	v_mfma_i32_16x16x64_i8 v[164:167], v[64:67], v[128:131], 0
	v_mfma_i32_16x16x64_i8 v[164:167], v[60:63], v[124:127], v[164:167]
	v_mfma_i32_16x16x64_i8 v[160:163], v[60:63], v[140:143], 0
	v_mfma_i32_16x16x64_i8 v[160:163], v[64:67], v[188:191], v[160:163]
	v_mfma_i32_16x16x64_i8 v[168:171], v[52:55], v[188:191], 0
	v_mfma_i32_16x16x64_i8 v[168:171], v[44:47], v[140:143], v[168:171]
	v_mfma_i32_16x16x64_i8 v[156:159], v[44:47], v[192:195], 0
	v_mfma_i32_16x16x64_i8 v[156:159], v[52:55], v[196:199], v[156:159]
	v_mfma_i32_16x16x64_i8 v[152:155], v[64:67], v[196:199], 0
	v_mfma_i32_16x16x64_i8 v[152:155], v[60:63], v[192:195], v[152:155]
	v_mfma_i32_16x16x64_i8 v[144:147], v[60:63], v[216:219], 0
	v_mfma_i32_16x16x64_i8 v[144:147], v[64:67], v[220:223], v[144:147]
	v_mfma_i32_16x16x64_i8 v[148:151], v[52:55], v[220:223], 0
	v_mfma_i32_16x16x64_i8 v[148:151], v[44:47], v[216:219], v[148:151]
	v_mfma_i32_16x16x64_i8 v[104:107], v[84:87], v[216:219], 0
	v_mfma_i32_16x16x64_i8 v[104:107], v[88:91], v[220:223], v[104:107]
	v_mfma_i32_16x16x64_i8 v[136:139], v[88:91], v[128:131], 0
	v_mfma_i32_16x16x64_i8 v[136:139], v[84:87], v[124:127], v[136:139]
	v_mfma_i32_16x16x64_i8 v[120:123], v[92:95], v[124:127], 0
	v_mfma_i32_16x16x64_i8 v[120:123], v[100:103], v[128:131], v[120:123]
	v_mfma_i32_16x16x64_i8 v[116:119], v[100:103], v[188:191], 0
	v_mfma_i32_16x16x64_i8 v[116:119], v[92:95], v[140:143], v[116:119]
	v_mfma_i32_16x16x64_i8 v[108:111], v[92:95], v[192:195], 0
	v_mfma_i32_16x16x64_i8 v[108:111], v[100:103], v[196:199], v[108:111]
	v_mfma_i32_16x16x64_i8 v[112:115], v[88:91], v[196:199], 0
	v_mfma_i32_16x16x64_i8 v[112:115], v[84:87], v[192:195], v[112:115]
	v_mfma_i32_16x16x64_i8 v[124:127], v[84:87], v[140:143], 0
	v_mfma_i32_16x16x64_i8 v[124:127], v[88:91], v[188:191], v[124:127]
	v_mfma_i32_16x16x64_i8 v[96:99], v[92:95], v[216:219], 0
	v_mfma_i32_16x16x64_i8 v[96:99], v[100:103], v[220:223], v[96:99]
	s_barrier
	s_add_i32 s8, s84, s12
	v_lshl_add_u64 v[200:201], s[82:83], 0, v[178:179]
	s_mov_b32 m0, s8
	ds_read_b128 v[128:131], v215 offset:16384
	ds_read_b128 v[132:135], v215 offset:17408
	ds_read_b128 v[140:143], v215 offset:18432
	ds_read_b128 v[188:191], v215 offset:19456
	ds_read_b128 v[192:195], v215 offset:20480
	ds_read_b128 v[196:199], v215 offset:21504
	ds_read_b128 v[216:219], v215 offset:22528
	ds_read_b128 v[220:223], v215 offset:23552
	global_load_lds_dwordx4 v[200:201], off
	s_add_i32 m0, s8, 0x2000
	s_add_u32 s8, s82, 0x40000
	v_lshl_add_u64 v[206:207], s[82:83], 0, v[182:183]
	s_addc_u32 s9, s83, 0
	s_add_i32 s10, s10, s12
	global_load_lds_dwordx4 v[206:207], off
	v_lshl_add_u64 v[2:3], s[8:9], 0, v[178:179]
	s_mov_b32 m0, s10
	v_lshl_add_u64 v[210:211], vcc, 0, v[176:177]
	global_load_lds_dwordx4 v[2:3], off
	v_lshl_add_u64 v[2:3], s[8:9], 0, v[182:183]
	s_add_i32 m0, s10, 0x2000
	v_lshl_add_u64 v[224:225], vcc, 0, v[180:181]
	global_load_lds_dwordx4 v[2:3], off
	s_mov_b32 m0, s13
	s_nop 0
	global_load_lds_dwordx4 v[210:211], off
	s_mov_b32 m0, s66
	s_nop 0
	global_load_lds_dwordx4 v[224:225], off
	s_waitcnt vmcnt(8)
	s_waitcnt lgkmcnt(0)
	s_barrier
	s_waitcnt lgkmcnt(0)
	v_mfma_i32_16x16x64_i8 v[80:83], v[44:47], v[128:131], 0
	v_mfma_i32_16x16x64_i8 v[80:83], v[52:55], v[132:135], v[80:83]
	v_mfma_i32_16x16x64_i8 v[72:75], v[64:67], v[132:135], 0
	v_mfma_i32_16x16x64_i8 v[72:75], v[60:63], v[128:131], v[72:75]
	v_mfma_i32_16x16x64_i8 v[68:71], v[60:63], v[140:143], 0
	v_mfma_i32_16x16x64_i8 v[68:71], v[64:67], v[188:191], v[68:71]
	v_mfma_i32_16x16x64_i8 v[76:79], v[52:55], v[188:191], 0
	v_mfma_i32_16x16x64_i8 v[76:79], v[44:47], v[140:143], v[76:79]
	v_mfma_i32_16x16x64_i8 v[56:59], v[44:47], v[192:195], 0
	v_mfma_i32_16x16x64_i8 v[56:59], v[52:55], v[196:199], v[56:59]
	v_mfma_i32_16x16x64_i8 v[48:51], v[64:67], v[196:199], 0
	v_mfma_i32_16x16x64_i8 v[48:51], v[60:63], v[192:195], v[48:51]
	v_mfma_i32_16x16x64_i8 v[36:39], v[60:63], v[216:219], 0
	v_mfma_i32_16x16x64_i8 v[36:39], v[64:67], v[220:223], v[36:39]
	v_mfma_i32_16x16x64_i8 v[40:43], v[52:55], v[220:223], 0
	v_mfma_i32_16x16x64_i8 v[40:43], v[44:47], v[216:219], v[40:43]
	v_mfma_i32_16x16x64_i8 v[2:5], v[92:95], v[216:219], 0
	v_mfma_i32_16x16x64_i8 v[2:5], v[100:103], v[220:223], v[2:5]
	v_mfma_i32_16x16x64_i8 v[24:27], v[100:103], v[132:135], 0
	v_mfma_i32_16x16x64_i8 v[24:27], v[92:95], v[128:131], v[24:27]
	v_mfma_i32_16x16x64_i8 v[32:35], v[84:87], v[128:131], 0
	v_mfma_i32_16x16x64_i8 v[32:35], v[88:91], v[132:135], v[32:35]
	v_mfma_i32_16x16x64_i8 v[28:31], v[88:91], v[188:191], 0
	v_mfma_i32_16x16x64_i8 v[28:31], v[84:87], v[140:143], v[28:31]
	v_mfma_i32_16x16x64_i8 v[20:23], v[92:95], v[140:143], 0
	v_mfma_i32_16x16x64_i8 v[20:23], v[100:103], v[188:191], v[20:23]
	v_mfma_i32_16x16x64_i8 v[12:15], v[100:103], v[196:199], 0
	v_mfma_i32_16x16x64_i8 v[12:15], v[92:95], v[192:195], v[12:15]
	v_mfma_i32_16x16x64_i8 v[16:19], v[84:87], v[192:195], 0
	v_mfma_i32_16x16x64_i8 v[16:19], v[88:91], v[196:199], v[16:19]
	v_mfma_i32_16x16x64_i8 v[8:11], v[88:91], v[220:223], 0
	v_mfma_i32_16x16x64_i8 v[8:11], v[84:87], v[216:219], v[8:11]
	s_barrier
; #define PG8_STAGE(bufoff, gbase, voff) do { _Pragma("unroll") for (int _i = 0; _i < 2; ++_i) \
;         __builtin_amdgcn_global_load_lds((const unsigned*)((const char*)(gbase) + (voff)[_i]), (PG8_LAS unsigned*)(lds + (bufoff) + ldsw + _i * 8192), 16, 0, 0); } while (0)
; #define PG8_LDA(dst, b, h) do { _Pragma("unroll") for (int m = 0; m < 4; ++m) _Pragma("unroll") for (int k = 0; k < 2; ++k) dst[m][k] = *(const PG8_LAS bf16x8*)(lds + PG8_SA(b, h) + aoff + m * 2048 + k * 1024); } while (0)
; #define PG8_LDB(dst, b, h) do { _Pragma("unroll") for (int n = 0; n < 2; ++n) _Pragma("unroll") for (int k = 0; k < 2; ++k) dst[n][k] = *(const PG8_LAS bf16x8*)(lds + PG8_SB(b, h) + boff + n * 2048 + k * 1024); } while (0)
; #define PG8_MMA(ai, bj, At, Bt) do { __builtin_amdgcn_s_setprio(1); _Pragma("unroll") for (int m = 0; m < 4; ++m) _Pragma("unroll") for (int n = 0; n < 2; ++n) _Pragma("unroll") for (int k = 0; k < 2; ++k) \
;         acc[ai][bj][m][n] = mma16<Epi::I8>(Bt[n][k], At[m][k], acc[ai][bj][m][n]); __builtin_amdgcn_s_setprio(0); } while (0)
; #define PG8_WAIT_V(n) asm volatile("s_waitcnt vmcnt(" #n ")" ::: "memory")
; #define PG8_WAIT_L(n) asm volatile("s_waitcnt lgkmcnt(" #n ")" ::: "memory")
; #define PG8_BAR __builtin_amdgcn_s_barrier()
; #define PG8_SCHED __builtin_amdgcn_sched_barrier(0)
; template <class Epi, class Sched, bool ALIGN_EPI = false, bool SP2 = false>
; __device__ __forceinline__ void gemm_phase(PG8_LAS unsigned char* lds, const Gemm g, const Sched& S, const Epi& E) {
;     ...
;             PG8_LDB(B0, 1, 0); PG8_LDB(B1, 1, 1); PG8_SCHED; PG8_LDA(At, 1, 0); PG8_STAGE(PG8_SA(0, 1), a2 + hstep, voffA);
;             PG8_WAIT_V(8); PG8_WAIT_L(0); PG8_BAR; PG8_MMA(0, 0, At, B0); PG8_MMA(0, 1, At, B1); PG8_BAR; PG8_SCHED;
;             PG8_LDA(At, 1, 1); PG8_STAGE(PG8_SB(1, 0), b3, voffB); PG8_STAGE(PG8_SB(1, 1), b3 + hstep, voffB); PG8_STAGE(PG8_SA(1, 0), a3, voffA);
;             PG8_WAIT_V(8); PG8_WAIT_L(0); PG8_BAR; PG8_MMA(1, 0, At, B0); PG8_MMA(1, 1, At, B1); PG8_BAR; PG8_SCHED;
	s_add_i32 s10, 0, 0x18000
	v_add_u32_e32 v0, s10, v214
	s_add_i32 s11, 0, 0x1c000
	ds_read_b128 v[44:47], v0
	ds_read_b128 v[52:55], v0 offset:1024
	ds_read_b128 v[60:63], v0 offset:2048
	ds_read_b128 v[64:67], v0 offset:3072
	v_add_u32_e32 v0, s11, v214
	ds_read_b128 v[84:87], v0
	ds_read_b128 v[88:91], v0 offset:1024
	ds_read_b128 v[92:95], v0 offset:2048
	ds_read_b128 v[100:103], v0 offset:3072
	s_add_u32 s8, vcc_lo, 0x40000
	s_addc_u32 s9, vcc_hi, 0
	s_mov_b32 m0, s67
	v_lshl_add_u64 v[6:7], s[8:9], 0, v[176:177]
	ds_read_b128 v[128:131], v215 offset:32768
	ds_read_b128 v[132:135], v215 offset:33792
	ds_read_b128 v[140:143], v215 offset:34816
	ds_read_b128 v[188:191], v215 offset:35840
	ds_read_b128 v[192:195], v215 offset:36864
	ds_read_b128 v[196:199], v215 offset:37888
	ds_read_b128 v[216:219], v215 offset:38912
	ds_read_b128 v[220:223], v215 offset:39936
	global_load_lds_dwordx4 v[6:7], off
	v_lshl_add_u64 v[6:7], s[8:9], 0, v[180:181]
	s_mov_b32 m0, s80
	s_nop 0
	global_load_lds_dwordx4 v[6:7], off
	s_waitcnt vmcnt(8)
	s_waitcnt lgkmcnt(0)
	s_barrier
	s_waitcnt lgkmcnt(0)
	v_mfma_i32_16x16x64_i8 v[172:175], v[44:47], v[128:131], v[172:175]
	v_mfma_i32_16x16x64_i8 v[172:175], v[52:55], v[132:135], v[172:175]
	v_mfma_i32_16x16x64_i8 v[164:167], v[60:63], v[128:131], v[164:167]
	v_mfma_i32_16x16x64_i8 v[164:167], v[64:67], v[132:135], v[164:167]
	v_mfma_i32_16x16x64_i8 v[160:163], v[60:63], v[140:143], v[160:163]
	v_mfma_i32_16x16x64_i8 v[160:163], v[64:67], v[188:191], v[160:163]
	v_mfma_i32_16x16x64_i8 v[168:171], v[44:47], v[140:143], v[168:171]
	v_mfma_i32_16x16x64_i8 v[168:171], v[52:55], v[188:191], v[168:171]
	v_mfma_i32_16x16x64_i8 v[156:159], v[44:47], v[192:195], v[156:159]
	v_mfma_i32_16x16x64_i8 v[156:159], v[52:55], v[196:199], v[156:159]
	v_mfma_i32_16x16x64_i8 v[152:155], v[60:63], v[192:195], v[152:155]
	v_mfma_i32_16x16x64_i8 v[152:155], v[64:67], v[196:199], v[152:155]
	v_mfma_i32_16x16x64_i8 v[144:147], v[60:63], v[216:219], v[144:147]
	v_mfma_i32_16x16x64_i8 v[144:147], v[64:67], v[220:223], v[144:147]
	v_mfma_i32_16x16x64_i8 v[148:151], v[44:47], v[216:219], v[148:151]
	v_mfma_i32_16x16x64_i8 v[148:151], v[52:55], v[220:223], v[148:151]
	v_mfma_i32_16x16x64_i8 v[136:139], v[84:87], v[128:131], v[136:139]
	v_mfma_i32_16x16x64_i8 v[136:139], v[88:91], v[132:135], v[136:139]
	v_mfma_i32_16x16x64_i8 v[120:123], v[92:95], v[128:131], v[120:123]
	v_mfma_i32_16x16x64_i8 v[120:123], v[100:103], v[132:135], v[120:123]
	v_mfma_i32_16x16x64_i8 v[116:119], v[92:95], v[140:143], v[116:119]
	v_mfma_i32_16x16x64_i8 v[116:119], v[100:103], v[188:191], v[116:119]
	v_mfma_i32_16x16x64_i8 v[124:127], v[84:87], v[140:143], v[124:127]
	v_mfma_i32_16x16x64_i8 v[132:135], v[88:91], v[188:191], v[124:127]
	v_mfma_i32_16x16x64_i8 v[112:115], v[84:87], v[192:195], v[112:115]
	v_mfma_i32_16x16x64_i8 v[112:115], v[88:91], v[196:199], v[112:115]
	v_mfma_i32_16x16x64_i8 v[108:111], v[92:95], v[192:195], v[108:111]
	v_mfma_i32_16x16x64_i8 v[108:111], v[100:103], v[196:199], v[108:111]
	v_mfma_i32_16x16x64_i8 v[96:99], v[92:95], v[216:219], v[96:99]
	v_mfma_i32_16x16x64_i8 v[96:99], v[100:103], v[220:223], v[96:99]
	v_mfma_i32_16x16x64_i8 v[104:107], v[84:87], v[216:219], v[104:107]
	v_mfma_i32_16x16x64_i8 v[104:107], v[88:91], v[220:223], v[104:107]
	s_barrier
	s_add_i32 s8, s10, s12
	v_lshl_add_u64 v[6:7], v[200:201], 0, s[92:93]
	s_mov_b32 m0, s8
	ds_read_b128 v[124:127], v215 offset:49152
	ds_read_b128 v[128:131], v215 offset:50176
	ds_read_b128 v[140:143], v215 offset:51200
	ds_read_b128 v[188:191], v215 offset:52224
	ds_read_b128 v[192:195], v215 offset:53248
	ds_read_b128 v[196:199], v215 offset:54272
	ds_read_b128 v[216:219], v215 offset:55296
	ds_read_b128 v[220:223], v215 offset:56320
	global_load_lds_dwordx4 v[6:7], off
	s_add_i32 m0, s8, 0x2000
	s_add_u32 s8, s82, 0x40080
	v_lshl_add_u64 v[6:7], v[206:207], 0, s[92:93]
	s_addc_u32 s9, s83, 0
	s_add_i32 s10, s11, s12
	global_load_lds_dwordx4 v[6:7], off
	v_lshl_add_u64 v[6:7], s[8:9], 0, v[178:179]
	s_mov_b32 m0, s10
	s_nop 0
	global_load_lds_dwordx4 v[6:7], off
	v_lshl_add_u64 v[6:7], s[8:9], 0, v[182:183]
	s_add_i32 m0, s10, 0x2000
	s_nop 0
	global_load_lds_dwordx4 v[6:7], off
	v_lshl_add_u64 v[6:7], v[210:211], 0, s[92:93]
	s_mov_b32 m0, s58
	s_nop 0
	global_load_lds_dwordx4 v[6:7], off
	v_lshl_add_u64 v[6:7], v[224:225], 0, s[92:93]
	s_mov_b32 m0, s4
	s_nop 0
	global_load_lds_dwordx4 v[6:7], off
	s_waitcnt vmcnt(8)
	s_waitcnt lgkmcnt(0)
	s_barrier
	s_waitcnt lgkmcnt(0)
	v_mfma_i32_16x16x64_i8 v[80:83], v[44:47], v[124:127], v[80:83]
	v_mfma_i32_16x16x64_i8 v[80:83], v[52:55], v[128:131], v[80:83]
	v_mfma_i32_16x16x64_i8 v[72:75], v[60:63], v[124:127], v[72:75]
	v_mfma_i32_16x16x64_i8 v[72:75], v[64:67], v[128:131], v[72:75]
	v_mfma_i32_16x16x64_i8 v[68:71], v[60:63], v[140:143], v[68:71]
	v_mfma_i32_16x16x64_i8 v[68:71], v[64:67], v[188:191], v[68:71]
	v_mfma_i32_16x16x64_i8 v[76:79], v[44:47], v[140:143], v[76:79]
	v_mfma_i32_16x16x64_i8 v[76:79], v[52:55], v[188:191], v[76:79]
	v_mfma_i32_16x16x64_i8 v[56:59], v[44:47], v[192:195], v[56:59]
	v_mfma_i32_16x16x64_i8 v[56:59], v[52:55], v[196:199], v[56:59]
	v_mfma_i32_16x16x64_i8 v[48:51], v[60:63], v[192:195], v[48:51]
	v_mfma_i32_16x16x64_i8 v[48:51], v[64:67], v[196:199], v[48:51]
	v_mfma_i32_16x16x64_i8 v[36:39], v[60:63], v[216:219], v[36:39]
	v_mfma_i32_16x16x64_i8 v[36:39], v[64:67], v[220:223], v[36:39]
	v_mfma_i32_16x16x64_i8 v[40:43], v[44:47], v[216:219], v[40:43]
	v_mfma_i32_16x16x64_i8 v[40:43], v[52:55], v[220:223], v[40:43]
	v_mfma_i32_16x16x64_i8 v[32:35], v[84:87], v[124:127], v[32:35]
	v_mfma_i32_16x16x64_i8 v[32:35], v[88:91], v[128:131], v[32:35]
	v_mfma_i32_16x16x64_i8 v[24:27], v[92:95], v[124:127], v[24:27]
	v_mfma_i32_16x16x64_i8 v[24:27], v[100:103], v[128:131], v[24:27]
	v_mfma_i32_16x16x64_i8 v[20:23], v[92:95], v[140:143], v[20:23]
	v_mfma_i32_16x16x64_i8 v[20:23], v[100:103], v[188:191], v[20:23]
	v_mfma_i32_16x16x64_i8 v[28:31], v[84:87], v[140:143], v[28:31]
	v_mfma_i32_16x16x64_i8 v[28:31], v[88:91], v[188:191], v[28:31]
	v_mfma_i32_16x16x64_i8 v[16:19], v[84:87], v[192:195], v[16:19]
	v_mfma_i32_16x16x64_i8 v[16:19], v[88:91], v[196:199], v[16:19]
	v_mfma_i32_16x16x64_i8 v[12:15], v[92:95], v[192:195], v[12:15]
	v_mfma_i32_16x16x64_i8 v[12:15], v[100:103], v[196:199], v[12:15]
	v_mfma_i32_16x16x64_i8 v[2:5], v[92:95], v[216:219], v[2:5]
	v_mfma_i32_16x16x64_i8 v[6:9], v[84:87], v[216:219], v[8:11]
	v_mfma_i32_16x16x64_i8 v[8:11], v[88:91], v[220:223], v[6:9]
	v_mfma_i32_16x16x64_i8 v[4:7], v[100:103], v[220:223], v[2:5]
	s_barrier
	s_add_i32 s5, s5, 2
	s_add_u32 s85, s85, 0x100
	s_addc_u32 s68, s68, 0
	s_cmp_gt_u32 s5, 13
	s_mov_b64 s[8:9], s[70:71]
	s_cbranch_scc0 .LBB0_385
	s_branch .Lpeelx385
